# P4 prompt rows (gated RMSNorm of the SSD half) hand-written: norm weights / D loaded once per wave, next row always in flight, packed f32 math, DPP reduction
# speedup vs baseline: 1.0315x; 1.0064x over previous
; __device__ __forceinline__ float siluf_(float x) { return x * __builtin_amdgcn_rcpf(1.f + __expf(-x)); }
; __device__ __forceinline__ void mix_finalize_ssd(size_t row, bf16_t* MIX, const bf16_t* XBC, const bf16_t* PROJ, const float* d_skip, const float* ssd_norm_w, int lane, bf16_t* ssd_dst) {
;     bf16_t* mp = MIX + row * DMIX;
;     {
;         u32x4 yv[4], xv[4], zv[4]; float dsk[4];
; #pragma unroll
;         for (int k = 0; k < 4; ++k) { const int c = (k * 64 + lane) * 8;
;             yv[k] = *(const u32x4*)(mp + c); xv[k] = *(const u32x4*)(XBC + row * XBCW + c); zv[k] = *(const u32x4*)(PROJ + row * NPROJ + CZ + c);
;             dsk[k] = d_skip[c >> 6]; }
;         float s = 0.f;
; #pragma unroll
;         for (int k = 0; k < 4; ++k) { float f[8], xf[8], zf[8]; unpack8(yv[k], f); unpack8(xv[k], xf); unpack8(zv[k], zf);
; #pragma unroll
;             for (int e = 0; e < 8; ++e) { f[e] = (f[e] + dsk[k] * xf[e]) * siluf_(zf[e]); s += f[e] * f[e]; }
;             yv[k] = pack8(f); }
; __global__ void __launch_bounds__(512, 2) mk_fwd(Args args) {
;     ...
;         for (int m = bx * 8 + wave; m < MP; m += G * 8) mix_finalize_ssd((size_t)m, MIX, XBC, PROJ, d_skip, ssd_norm_w, lane, (psel == 3) ? XN + (size_t)m * DM : MIX + (size_t)m * DMIX);
.LBB0_545:
	s_cmp_lt_i32 s88, 5
	s_cselect_b64 s[4:5], -1, 0
	s_and_b64 s[0:1], s[4:5], s[0:1]
	s_andn2_b64 vcc, exec, s[0:1]
	s_cbranch_vccnz .LBB0_561
	s_mov_b64 s[8:9], s[96:97]
	s_waitcnt vmcnt(0)
	v_mov_b32_e32 v0, v212
	s_lshl_b32 s4, s2, 3
	v_readfirstlane_b32 s16, v0
	s_ashr_i32 s3, s16, 6
	s_add_i32 s10, s3, s4
	s_cmpk_gt_i32 s10, 0x1fff
	v_and_b32_e32 v54, 63, v0
	s_cbranch_scc1 .LBB0_556
	s_load_dwordx2 s[12:13], s[8:9], 0xd0
	s_load_dwordx4 s[4:7], s[8:9], 0x60
	v_lshlrev_b32_e32 v50, 4, v54
	v_lshlrev_b32_e32 v51, 5, v54
	v_lshrrev_b32_e32 v52, 3, v54
	v_lshlrev_b32_e32 v52, 2, v52
	v_mov_b32_e32 v46, 0xbfb8aa3b
	v_mov_b32_e32 v47, 1.0
	v_mov_b32_e32 v48, 0x3727c5ac
	s_waitcnt lgkmcnt(0)
	s_add_u32 s22, s6, 0x1000
	s_addc_u32 s23, s7, 0
	global_load_dwordx4 v[0:3], v51, s[6:7] offset:0
	global_load_dwordx4 v[4:7], v51, s[6:7] offset:16
	global_load_dwordx4 v[8:11], v51, s[6:7] offset:2048
	global_load_dwordx4 v[12:15], v51, s[6:7] offset:2064
	global_load_dwordx4 v[16:19], v51, s[22:23] offset:0
	global_load_dwordx4 v[20:23], v51, s[22:23] offset:16
	global_load_dwordx4 v[24:27], v51, s[22:23] offset:2048
	global_load_dwordx4 v[28:31], v51, s[22:23] offset:2064
	global_load_dword v32, v52, s[4:5] offset:0
	global_load_dword v33, v52, s[4:5] offset:32
	global_load_dword v34, v52, s[4:5] offset:64
	global_load_dword v35, v52, s[4:5] offset:96
	s_lshl_b32 s17, s10, 13
	s_add_u32 s14, s12, 0x1acd0000
	s_addc_u32 s15, s13, 0
	s_add_u32 s14, s14, s17
	s_addc_u32 s15, s15, 0
	s_mul_i32 s17, s10, 0x1800
	s_add_u32 s18, s12, 0x135d0000
	s_addc_u32 s19, s13, 0
	s_add_u32 s18, s18, s17
	s_addc_u32 s19, s19, 0
	s_mul_i32 s17, s10, 0x4a00
	s_add_u32 s20, s12, 0x9890000
	s_addc_u32 s21, s13, 0
	s_add_u32 s20, s20, s17
	s_addc_u32 s21, s21, 0
	global_load_dwordx4 v[56:59], v50, s[14:15] offset:0
	global_load_dwordx4 v[60:63], v50, s[14:15] offset:1024
	global_load_dwordx4 v[64:67], v50, s[14:15] offset:2048
	global_load_dwordx4 v[68:71], v50, s[14:15] offset:3072
	global_load_dwordx4 v[72:75], v50, s[18:19] offset:0
	global_load_dwordx4 v[76:79], v50, s[18:19] offset:1024
	global_load_dwordx4 v[80:83], v50, s[18:19] offset:2048
	global_load_dwordx4 v[84:87], v50, s[18:19] offset:3072
	global_load_dwordx4 v[88:91], v50, s[20:21] offset:0
	global_load_dwordx4 v[92:95], v50, s[20:21] offset:1024
	global_load_dwordx4 v[96:99], v50, s[20:21] offset:2048
	global_load_dwordx4 v[100:103], v50, s[20:21] offset:3072
	s_mov_b32 s26, s14
	s_mov_b32 s27, s15
	s_add_u32 s14, s14, 0x1000000
	s_addc_u32 s15, s15, 0
	s_add_u32 s18, s18, 0xc00000
	s_addc_u32 s19, s19, 0
	s_add_u32 s20, s20, 0x2500000
	s_addc_u32 s21, s21, 0
	global_load_dwordx4 v[104:107], v50, s[14:15] offset:0
	global_load_dwordx4 v[108:111], v50, s[14:15] offset:1024
	global_load_dwordx4 v[112:115], v50, s[14:15] offset:2048
	global_load_dwordx4 v[116:119], v50, s[14:15] offset:3072
	global_load_dwordx4 v[120:123], v50, s[18:19] offset:0
	global_load_dwordx4 v[124:127], v50, s[18:19] offset:1024
	global_load_dwordx4 v[128:131], v50, s[18:19] offset:2048
	global_load_dwordx4 v[132:135], v50, s[18:19] offset:3072
	global_load_dwordx4 v[136:139], v50, s[20:21] offset:0
	global_load_dwordx4 v[140:143], v50, s[20:21] offset:1024
	global_load_dwordx4 v[144:147], v50, s[20:21] offset:2048
	global_load_dwordx4 v[148:151], v50, s[20:21] offset:3072
	s_mov_b32 s12, s14
	s_mov_b32 s13, s15
	s_add_u32 s14, s14, 0x1000000
	s_addc_u32 s15, s15, 0
	s_add_u32 s18, s18, 0xc00000
	s_addc_u32 s19, s19, 0
	s_add_u32 s20, s20, 0x2500000
	s_addc_u32 s21, s21, 0
	s_waitcnt vmcnt(12)
	v_mov_b32_e32 v44, 0
	v_mov_b32_e32 v45, 0
	v_lshlrev_b32_e32 v184, 16, v56
	v_and_b32_e32 v185, 0xffff0000, v56
	v_lshlrev_b32_e32 v186, 16, v57
	v_and_b32_e32 v187, 0xffff0000, v57
	v_lshlrev_b32_e32 v188, 16, v58
	v_and_b32_e32 v189, 0xffff0000, v58
	v_lshlrev_b32_e32 v190, 16, v59
	v_and_b32_e32 v191, 0xffff0000, v59
	v_lshlrev_b32_e32 v192, 16, v72
	v_and_b32_e32 v193, 0xffff0000, v72
	v_lshlrev_b32_e32 v194, 16, v73
	v_and_b32_e32 v195, 0xffff0000, v73
	v_lshlrev_b32_e32 v196, 16, v74
	v_and_b32_e32 v197, 0xffff0000, v74
	v_lshlrev_b32_e32 v198, 16, v75
	v_and_b32_e32 v199, 0xffff0000, v75
	v_lshlrev_b32_e32 v200, 16, v88
	v_and_b32_e32 v201, 0xffff0000, v88
	v_lshlrev_b32_e32 v202, 16, v89
	v_and_b32_e32 v203, 0xffff0000, v89
	v_lshlrev_b32_e32 v204, 16, v90
	v_and_b32_e32 v205, 0xffff0000, v90
	v_lshlrev_b32_e32 v206, 16, v91
	v_and_b32_e32 v207, 0xffff0000, v91
	v_pk_fma_f32 v[184:185], v[192:193], v[32:33], v[184:185] op_sel:[0,0,0] op_sel_hi:[1,0,1]
	v_pk_fma_f32 v[186:187], v[194:195], v[32:33], v[186:187] op_sel:[0,0,0] op_sel_hi:[1,0,1]
	v_pk_fma_f32 v[188:189], v[196:197], v[32:33], v[188:189] op_sel:[0,0,0] op_sel_hi:[1,0,1]
	v_pk_fma_f32 v[190:191], v[198:199], v[32:33], v[190:191] op_sel:[0,0,0] op_sel_hi:[1,0,1]
	v_pk_mul_f32 v[36:37], v[200:201], v[46:47] op_sel:[0,0] op_sel_hi:[1,0]
	v_pk_mul_f32 v[38:39], v[202:203], v[46:47] op_sel:[0,0] op_sel_hi:[1,0]
	v_pk_mul_f32 v[40:41], v[204:205], v[46:47] op_sel:[0,0] op_sel_hi:[1,0]
	v_pk_mul_f32 v[42:43], v[206:207], v[46:47] op_sel:[0,0] op_sel_hi:[1,0]
	v_exp_f32_e32 v36, v36
	v_exp_f32_e32 v37, v37
	v_exp_f32_e32 v38, v38
	v_exp_f32_e32 v39, v39
	v_exp_f32_e32 v40, v40
	v_exp_f32_e32 v41, v41
	v_exp_f32_e32 v42, v42
	v_exp_f32_e32 v43, v43
	v_pk_add_f32 v[36:37], v[36:37], v[46:47] op_sel:[0,1] op_sel_hi:[1,1]
	v_pk_add_f32 v[38:39], v[38:39], v[46:47] op_sel:[0,1] op_sel_hi:[1,1]
	v_pk_add_f32 v[40:41], v[40:41], v[46:47] op_sel:[0,1] op_sel_hi:[1,1]
	v_pk_add_f32 v[42:43], v[42:43], v[46:47] op_sel:[0,1] op_sel_hi:[1,1]
	v_rcp_f32_e32 v36, v36
; __device__ __forceinline__ float siluf_(float x) { return x * __builtin_amdgcn_rcpf(1.f + __expf(-x)); }
; __device__ __forceinline__ void mix_finalize_ssd(size_t row, bf16_t* MIX, const bf16_t* XBC, const bf16_t* PROJ, const float* d_skip, const float* ssd_norm_w, int lane, bf16_t* ssd_dst) {
;     ...
;         for (int k = 0; k < 4; ++k) { float f[8], xf[8], zf[8]; unpack8(yv[k], f); unpack8(xv[k], xf); unpack8(zv[k], zf);
; #pragma unroll
;             for (int e = 0; e < 8; ++e) { f[e] = (f[e] + dsk[k] * xf[e]) * siluf_(zf[e]); s += f[e] * f[e]; }
;             yv[k] = pack8(f); }
	v_rcp_f32_e32 v37, v37
	v_rcp_f32_e32 v38, v38
	v_rcp_f32_e32 v39, v39
	v_rcp_f32_e32 v40, v40
	v_rcp_f32_e32 v41, v41
	v_rcp_f32_e32 v42, v42
	v_rcp_f32_e32 v43, v43
	v_pk_mul_f32 v[36:37], v[200:201], v[36:37]
	v_pk_mul_f32 v[38:39], v[202:203], v[38:39]
	v_pk_mul_f32 v[40:41], v[204:205], v[40:41]
	v_pk_mul_f32 v[42:43], v[206:207], v[42:43]
	v_pk_mul_f32 v[184:185], v[184:185], v[36:37]
	v_pk_mul_f32 v[186:187], v[186:187], v[38:39]
	v_pk_mul_f32 v[188:189], v[188:189], v[40:41]
	v_pk_mul_f32 v[190:191], v[190:191], v[42:43]
	v_pk_fma_f32 v[44:45], v[184:185], v[184:185], v[44:45]
	v_pk_fma_f32 v[44:45], v[186:187], v[186:187], v[44:45]
	v_pk_fma_f32 v[44:45], v[188:189], v[188:189], v[44:45]
	v_pk_fma_f32 v[44:45], v[190:191], v[190:191], v[44:45]
	v_cvt_pk_bf16_f32 v152, v184, v185
	v_cvt_pk_bf16_f32 v153, v186, v187
	v_cvt_pk_bf16_f32 v154, v188, v189
	v_cvt_pk_bf16_f32 v155, v190, v191
	v_lshlrev_b32_e32 v184, 16, v60
	v_and_b32_e32 v185, 0xffff0000, v60
	v_lshlrev_b32_e32 v186, 16, v61
	v_and_b32_e32 v187, 0xffff0000, v61
	v_lshlrev_b32_e32 v188, 16, v62
	v_and_b32_e32 v189, 0xffff0000, v62
	v_lshlrev_b32_e32 v190, 16, v63
	v_and_b32_e32 v191, 0xffff0000, v63
	v_lshlrev_b32_e32 v192, 16, v76
	v_and_b32_e32 v193, 0xffff0000, v76
	v_lshlrev_b32_e32 v194, 16, v77
	v_and_b32_e32 v195, 0xffff0000, v77
	v_lshlrev_b32_e32 v196, 16, v78
	v_and_b32_e32 v197, 0xffff0000, v78
	v_lshlrev_b32_e32 v198, 16, v79
	v_and_b32_e32 v199, 0xffff0000, v79
	v_lshlrev_b32_e32 v200, 16, v92
	v_and_b32_e32 v201, 0xffff0000, v92
	v_lshlrev_b32_e32 v202, 16, v93
	v_and_b32_e32 v203, 0xffff0000, v93
	v_lshlrev_b32_e32 v204, 16, v94
	v_and_b32_e32 v205, 0xffff0000, v94
	v_lshlrev_b32_e32 v206, 16, v95
	v_and_b32_e32 v207, 0xffff0000, v95
	v_pk_fma_f32 v[184:185], v[192:193], v[32:33], v[184:185] op_sel:[0,1,0] op_sel_hi:[1,1,1]
	v_pk_fma_f32 v[186:187], v[194:195], v[32:33], v[186:187] op_sel:[0,1,0] op_sel_hi:[1,1,1]
	v_pk_fma_f32 v[188:189], v[196:197], v[32:33], v[188:189] op_sel:[0,1,0] op_sel_hi:[1,1,1]
	v_pk_fma_f32 v[190:191], v[198:199], v[32:33], v[190:191] op_sel:[0,1,0] op_sel_hi:[1,1,1]
	v_pk_mul_f32 v[36:37], v[200:201], v[46:47] op_sel:[0,0] op_sel_hi:[1,0]
	v_pk_mul_f32 v[38:39], v[202:203], v[46:47] op_sel:[0,0] op_sel_hi:[1,0]
	v_pk_mul_f32 v[40:41], v[204:205], v[46:47] op_sel:[0,0] op_sel_hi:[1,0]
	v_pk_mul_f32 v[42:43], v[206:207], v[46:47] op_sel:[0,0] op_sel_hi:[1,0]
	v_exp_f32_e32 v36, v36
	v_exp_f32_e32 v37, v37
	v_exp_f32_e32 v38, v38
	v_exp_f32_e32 v39, v39
	v_exp_f32_e32 v40, v40
	v_exp_f32_e32 v41, v41
	v_exp_f32_e32 v42, v42
	v_exp_f32_e32 v43, v43
	v_pk_add_f32 v[36:37], v[36:37], v[46:47] op_sel:[0,1] op_sel_hi:[1,1]
	v_pk_add_f32 v[38:39], v[38:39], v[46:47] op_sel:[0,1] op_sel_hi:[1,1]
	v_pk_add_f32 v[40:41], v[40:41], v[46:47] op_sel:[0,1] op_sel_hi:[1,1]
	v_pk_add_f32 v[42:43], v[42:43], v[46:47] op_sel:[0,1] op_sel_hi:[1,1]
	v_rcp_f32_e32 v36, v36
	v_rcp_f32_e32 v37, v37
	v_rcp_f32_e32 v38, v38
	v_rcp_f32_e32 v39, v39
	v_rcp_f32_e32 v40, v40
	v_rcp_f32_e32 v41, v41
	v_rcp_f32_e32 v42, v42
	v_rcp_f32_e32 v43, v43
	v_pk_mul_f32 v[36:37], v[200:201], v[36:37]
	v_pk_mul_f32 v[38:39], v[202:203], v[38:39]
	v_pk_mul_f32 v[40:41], v[204:205], v[40:41]
	v_pk_mul_f32 v[42:43], v[206:207], v[42:43]
	v_pk_mul_f32 v[184:185], v[184:185], v[36:37]
	v_pk_mul_f32 v[186:187], v[186:187], v[38:39]
	v_pk_mul_f32 v[188:189], v[188:189], v[40:41]
	v_pk_mul_f32 v[190:191], v[190:191], v[42:43]
	v_pk_fma_f32 v[44:45], v[184:185], v[184:185], v[44:45]
	v_pk_fma_f32 v[44:45], v[186:187], v[186:187], v[44:45]
	v_pk_fma_f32 v[44:45], v[188:189], v[188:189], v[44:45]
	v_pk_fma_f32 v[44:45], v[190:191], v[190:191], v[44:45]
	v_cvt_pk_bf16_f32 v156, v184, v185
	v_cvt_pk_bf16_f32 v157, v186, v187
	v_cvt_pk_bf16_f32 v158, v188, v189
	v_cvt_pk_bf16_f32 v159, v190, v191
	v_lshlrev_b32_e32 v184, 16, v64
	v_and_b32_e32 v185, 0xffff0000, v64
	v_lshlrev_b32_e32 v186, 16, v65
	v_and_b32_e32 v187, 0xffff0000, v65
	v_lshlrev_b32_e32 v188, 16, v66
	v_and_b32_e32 v189, 0xffff0000, v66
	v_lshlrev_b32_e32 v190, 16, v67
	v_and_b32_e32 v191, 0xffff0000, v67
	v_lshlrev_b32_e32 v192, 16, v80
	v_and_b32_e32 v193, 0xffff0000, v80
	v_lshlrev_b32_e32 v194, 16, v81
	v_and_b32_e32 v195, 0xffff0000, v81
	v_lshlrev_b32_e32 v196, 16, v82
	v_and_b32_e32 v197, 0xffff0000, v82
	v_lshlrev_b32_e32 v198, 16, v83
	v_and_b32_e32 v199, 0xffff0000, v83
	v_lshlrev_b32_e32 v200, 16, v96
	v_and_b32_e32 v201, 0xffff0000, v96
	v_lshlrev_b32_e32 v202, 16, v97
	v_and_b32_e32 v203, 0xffff0000, v97
	v_lshlrev_b32_e32 v204, 16, v98
	v_and_b32_e32 v205, 0xffff0000, v98
	v_lshlrev_b32_e32 v206, 16, v99
	v_and_b32_e32 v207, 0xffff0000, v99
	v_pk_fma_f32 v[184:185], v[192:193], v[34:35], v[184:185] op_sel:[0,0,0] op_sel_hi:[1,0,1]
	v_pk_fma_f32 v[186:187], v[194:195], v[34:35], v[186:187] op_sel:[0,0,0] op_sel_hi:[1,0,1]
	v_pk_fma_f32 v[188:189], v[196:197], v[34:35], v[188:189] op_sel:[0,0,0] op_sel_hi:[1,0,1]
	v_pk_fma_f32 v[190:191], v[198:199], v[34:35], v[190:191] op_sel:[0,0,0] op_sel_hi:[1,0,1]
	v_pk_mul_f32 v[36:37], v[200:201], v[46:47] op_sel:[0,0] op_sel_hi:[1,0]
	v_pk_mul_f32 v[38:39], v[202:203], v[46:47] op_sel:[0,0] op_sel_hi:[1,0]
	v_pk_mul_f32 v[40:41], v[204:205], v[46:47] op_sel:[0,0] op_sel_hi:[1,0]
	v_pk_mul_f32 v[42:43], v[206:207], v[46:47] op_sel:[0,0] op_sel_hi:[1,0]
	v_exp_f32_e32 v36, v36
	v_exp_f32_e32 v37, v37
	v_exp_f32_e32 v38, v38
	v_exp_f32_e32 v39, v39
	v_exp_f32_e32 v40, v40
	v_exp_f32_e32 v41, v41
	v_exp_f32_e32 v42, v42
	v_exp_f32_e32 v43, v43
	v_pk_add_f32 v[36:37], v[36:37], v[46:47] op_sel:[0,1] op_sel_hi:[1,1]
	v_pk_add_f32 v[38:39], v[38:39], v[46:47] op_sel:[0,1] op_sel_hi:[1,1]
; __device__ __forceinline__ float siluf_(float x) { return x * __builtin_amdgcn_rcpf(1.f + __expf(-x)); }
; __device__ __forceinline__ void mix_finalize_ssd(size_t row, bf16_t* MIX, const bf16_t* XBC, const bf16_t* PROJ, const float* d_skip, const float* ssd_norm_w, int lane, bf16_t* ssd_dst) {
;     ...
;         for (int k = 0; k < 4; ++k) { float f[8], xf[8], zf[8]; unpack8(yv[k], f); unpack8(xv[k], xf); unpack8(zv[k], zf);
; #pragma unroll
;             for (int e = 0; e < 8; ++e) { f[e] = (f[e] + dsk[k] * xf[e]) * siluf_(zf[e]); s += f[e] * f[e]; }
;             yv[k] = pack8(f); }
;         const float r = rsqrtf(wave_sum(s) * (1.f / DM) + EPS);
; #pragma unroll 1
;         for (int k = 0; k < 4; ++k) { const int c = (k * 64 + lane) * 8;
;             const f32x4 w0 = *(const f32x4*)(ssd_norm_w + c), w1 = *(const f32x4*)(ssd_norm_w + c + 4);
;             const u32x4 yk = (k == 0) ? yv[0] : (k == 1) ? yv[1] : (k == 2) ? yv[2] : yv[3];
;             float f[8]; unpack8(yk, f);
;             float o[8]; o[0] = f[0] * r * w0.x; o[1] = f[1] * r * w0.y; o[2] = f[2] * r * w0.z; o[3] = f[3] * r * w0.w;
;             o[4] = f[4] * r * w1.x; o[5] = f[5] * r * w1.y; o[6] = f[6] * r * w1.z; o[7] = f[7] * r * w1.w;
;             *(u32x4*)(ssd_dst + c) = pack8(o); }
	v_pk_add_f32 v[40:41], v[40:41], v[46:47] op_sel:[0,1] op_sel_hi:[1,1]
	v_pk_add_f32 v[42:43], v[42:43], v[46:47] op_sel:[0,1] op_sel_hi:[1,1]
	v_rcp_f32_e32 v36, v36
	v_rcp_f32_e32 v37, v37
	v_rcp_f32_e32 v38, v38
	v_rcp_f32_e32 v39, v39
	v_rcp_f32_e32 v40, v40
	v_rcp_f32_e32 v41, v41
	v_rcp_f32_e32 v42, v42
	v_rcp_f32_e32 v43, v43
	v_pk_mul_f32 v[36:37], v[200:201], v[36:37]
	v_pk_mul_f32 v[38:39], v[202:203], v[38:39]
	v_pk_mul_f32 v[40:41], v[204:205], v[40:41]
	v_pk_mul_f32 v[42:43], v[206:207], v[42:43]
	v_pk_mul_f32 v[184:185], v[184:185], v[36:37]
	v_pk_mul_f32 v[186:187], v[186:187], v[38:39]
	v_pk_mul_f32 v[188:189], v[188:189], v[40:41]
	v_pk_mul_f32 v[190:191], v[190:191], v[42:43]
	v_pk_fma_f32 v[44:45], v[184:185], v[184:185], v[44:45]
	v_pk_fma_f32 v[44:45], v[186:187], v[186:187], v[44:45]
	v_pk_fma_f32 v[44:45], v[188:189], v[188:189], v[44:45]
	v_pk_fma_f32 v[44:45], v[190:191], v[190:191], v[44:45]
	v_cvt_pk_bf16_f32 v160, v184, v185
	v_cvt_pk_bf16_f32 v161, v186, v187
	v_cvt_pk_bf16_f32 v162, v188, v189
	v_cvt_pk_bf16_f32 v163, v190, v191
	v_lshlrev_b32_e32 v184, 16, v68
	v_and_b32_e32 v185, 0xffff0000, v68
	v_lshlrev_b32_e32 v186, 16, v69
	v_and_b32_e32 v187, 0xffff0000, v69
	v_lshlrev_b32_e32 v188, 16, v70
	v_and_b32_e32 v189, 0xffff0000, v70
	v_lshlrev_b32_e32 v190, 16, v71
	v_and_b32_e32 v191, 0xffff0000, v71
	v_lshlrev_b32_e32 v192, 16, v84
	v_and_b32_e32 v193, 0xffff0000, v84
	v_lshlrev_b32_e32 v194, 16, v85
	v_and_b32_e32 v195, 0xffff0000, v85
	v_lshlrev_b32_e32 v196, 16, v86
	v_and_b32_e32 v197, 0xffff0000, v86
	v_lshlrev_b32_e32 v198, 16, v87
	v_and_b32_e32 v199, 0xffff0000, v87
	v_lshlrev_b32_e32 v200, 16, v100
	v_and_b32_e32 v201, 0xffff0000, v100
	v_lshlrev_b32_e32 v202, 16, v101
	v_and_b32_e32 v203, 0xffff0000, v101
	v_lshlrev_b32_e32 v204, 16, v102
	v_and_b32_e32 v205, 0xffff0000, v102
	v_lshlrev_b32_e32 v206, 16, v103
	v_and_b32_e32 v207, 0xffff0000, v103
	v_pk_fma_f32 v[184:185], v[192:193], v[34:35], v[184:185] op_sel:[0,1,0] op_sel_hi:[1,1,1]
	v_pk_fma_f32 v[186:187], v[194:195], v[34:35], v[186:187] op_sel:[0,1,0] op_sel_hi:[1,1,1]
	v_pk_fma_f32 v[188:189], v[196:197], v[34:35], v[188:189] op_sel:[0,1,0] op_sel_hi:[1,1,1]
	v_pk_fma_f32 v[190:191], v[198:199], v[34:35], v[190:191] op_sel:[0,1,0] op_sel_hi:[1,1,1]
	v_pk_mul_f32 v[36:37], v[200:201], v[46:47] op_sel:[0,0] op_sel_hi:[1,0]
	v_pk_mul_f32 v[38:39], v[202:203], v[46:47] op_sel:[0,0] op_sel_hi:[1,0]
	v_pk_mul_f32 v[40:41], v[204:205], v[46:47] op_sel:[0,0] op_sel_hi:[1,0]
	v_pk_mul_f32 v[42:43], v[206:207], v[46:47] op_sel:[0,0] op_sel_hi:[1,0]
	v_exp_f32_e32 v36, v36
	v_exp_f32_e32 v37, v37
	v_exp_f32_e32 v38, v38
	v_exp_f32_e32 v39, v39
	v_exp_f32_e32 v40, v40
	v_exp_f32_e32 v41, v41
	v_exp_f32_e32 v42, v42
	v_exp_f32_e32 v43, v43
	v_pk_add_f32 v[36:37], v[36:37], v[46:47] op_sel:[0,1] op_sel_hi:[1,1]
	v_pk_add_f32 v[38:39], v[38:39], v[46:47] op_sel:[0,1] op_sel_hi:[1,1]
	v_pk_add_f32 v[40:41], v[40:41], v[46:47] op_sel:[0,1] op_sel_hi:[1,1]
	v_pk_add_f32 v[42:43], v[42:43], v[46:47] op_sel:[0,1] op_sel_hi:[1,1]
	v_rcp_f32_e32 v36, v36
	v_rcp_f32_e32 v37, v37
	v_rcp_f32_e32 v38, v38
	v_rcp_f32_e32 v39, v39
	v_rcp_f32_e32 v40, v40
	v_rcp_f32_e32 v41, v41
	v_rcp_f32_e32 v42, v42
	v_rcp_f32_e32 v43, v43
	v_pk_mul_f32 v[36:37], v[200:201], v[36:37]
	v_pk_mul_f32 v[38:39], v[202:203], v[38:39]
	v_pk_mul_f32 v[40:41], v[204:205], v[40:41]
	v_pk_mul_f32 v[42:43], v[206:207], v[42:43]
	v_pk_mul_f32 v[184:185], v[184:185], v[36:37]
	v_pk_mul_f32 v[186:187], v[186:187], v[38:39]
	v_pk_mul_f32 v[188:189], v[188:189], v[40:41]
	v_pk_mul_f32 v[190:191], v[190:191], v[42:43]
	v_pk_fma_f32 v[44:45], v[184:185], v[184:185], v[44:45]
	v_pk_fma_f32 v[44:45], v[186:187], v[186:187], v[44:45]
	v_pk_fma_f32 v[44:45], v[188:189], v[188:189], v[44:45]
	v_pk_fma_f32 v[44:45], v[190:191], v[190:191], v[44:45]
	v_cvt_pk_bf16_f32 v164, v184, v185
	v_cvt_pk_bf16_f32 v165, v186, v187
	v_cvt_pk_bf16_f32 v166, v188, v189
	v_cvt_pk_bf16_f32 v167, v190, v191
	v_add_f32_e32 v208, v44, v45
	s_nop 1
	v_add_f32_dpp v209, v208, v208 quad_perm:[1,0,3,2] row_mask:0xf bank_mask:0xf
	s_nop 1
	v_add_f32_dpp v208, v209, v209 quad_perm:[2,3,0,1] row_mask:0xf bank_mask:0xf
	s_nop 1
	v_add_f32_dpp v209, v208, v208 row_half_mirror row_mask:0xf bank_mask:0xf
	s_nop 1
	v_add_f32_dpp v208, v209, v209 row_mirror row_mask:0xf bank_mask:0xf
	s_nop 1
	v_readlane_b32 s10, v208, 0
	v_readlane_b32 s11, v208, 16
	v_readlane_b32 s17, v208, 32
	v_readlane_b32 s24, v208, 48
	s_nop 3
	v_mov_b32_e32 v208, s10
	v_add_f32_e32 v208, s11, v208
	v_add_f32_e32 v208, s17, v208
	v_add_f32_e32 v208, s24, v208
	v_fmamk_f32 v208, v208, 0x3a000000, v48
	v_rsq_f32_e32 v49, v208
	s_nop 0
	v_lshlrev_b32_e32 v184, 16, v152
	v_and_b32_e32 v185, 0xffff0000, v152
	v_lshlrev_b32_e32 v186, 16, v153
	v_and_b32_e32 v187, 0xffff0000, v153
	v_lshlrev_b32_e32 v188, 16, v154
	v_and_b32_e32 v189, 0xffff0000, v154
	v_lshlrev_b32_e32 v190, 16, v155
	v_and_b32_e32 v191, 0xffff0000, v155
	v_pk_mul_f32 v[184:185], v[184:185], v[48:49] op_sel:[0,1] op_sel_hi:[1,1]
	v_pk_mul_f32 v[186:187], v[186:187], v[48:49] op_sel:[0,1] op_sel_hi:[1,1]
	v_pk_mul_f32 v[188:189], v[188:189], v[48:49] op_sel:[0,1] op_sel_hi:[1,1]
	v_pk_mul_f32 v[190:191], v[190:191], v[48:49] op_sel:[0,1] op_sel_hi:[1,1]
	v_pk_mul_f32 v[184:185], v[184:185], v[0:1]
	v_pk_mul_f32 v[186:187], v[186:187], v[2:3]
	v_pk_mul_f32 v[188:189], v[188:189], v[4:5]
	v_pk_mul_f32 v[190:191], v[190:191], v[6:7]
	v_cvt_pk_bf16_f32 v168, v184, v185
	v_cvt_pk_bf16_f32 v169, v186, v187
	v_cvt_pk_bf16_f32 v170, v188, v189
	v_cvt_pk_bf16_f32 v171, v190, v191
; __device__ __forceinline__ float siluf_(float x) { return x * __builtin_amdgcn_rcpf(1.f + __expf(-x)); }
; __device__ __forceinline__ void mix_finalize_ssd(size_t row, bf16_t* MIX, const bf16_t* XBC, const bf16_t* PROJ, const float* d_skip, const float* ssd_norm_w, int lane, bf16_t* ssd_dst) {
;     ...
;         for (int k = 0; k < 4; ++k) { const int c = (k * 64 + lane) * 8;
;             yv[k] = *(const u32x4*)(mp + c); xv[k] = *(const u32x4*)(XBC + row * XBCW + c); zv[k] = *(const u32x4*)(PROJ + row * NPROJ + CZ + c);
;             dsk[k] = d_skip[c >> 6]; }
;         float s = 0.f;
; #pragma unroll
;         for (int k = 0; k < 4; ++k) { float f[8], xf[8], zf[8]; unpack8(yv[k], f); unpack8(xv[k], xf); unpack8(zv[k], zf);
; #pragma unroll
;             for (int e = 0; e < 8; ++e) { f[e] = (f[e] + dsk[k] * xf[e]) * siluf_(zf[e]); s += f[e] * f[e]; }
;             yv[k] = pack8(f); }
;         const float r = rsqrtf(wave_sum(s) * (1.f / DM) + EPS);
; #pragma unroll 1
;         for (int k = 0; k < 4; ++k) { const int c = (k * 64 + lane) * 8;
;             const f32x4 w0 = *(const f32x4*)(ssd_norm_w + c), w1 = *(const f32x4*)(ssd_norm_w + c + 4);
;             const u32x4 yk = (k == 0) ? yv[0] : (k == 1) ? yv[1] : (k == 2) ? yv[2] : yv[3];
;             float f[8]; unpack8(yk, f);
;             float o[8]; o[0] = f[0] * r * w0.x; o[1] = f[1] * r * w0.y; o[2] = f[2] * r * w0.z; o[3] = f[3] * r * w0.w;
;             o[4] = f[4] * r * w1.x; o[5] = f[5] * r * w1.y; o[6] = f[6] * r * w1.z; o[7] = f[7] * r * w1.w;
;             *(u32x4*)(ssd_dst + c) = pack8(o); }
	global_store_dwordx4 v50, v[168:171], s[26:27] offset:0
	v_lshlrev_b32_e32 v184, 16, v156
	v_and_b32_e32 v185, 0xffff0000, v156
	v_lshlrev_b32_e32 v186, 16, v157
	v_and_b32_e32 v187, 0xffff0000, v157
	v_lshlrev_b32_e32 v188, 16, v158
	v_and_b32_e32 v189, 0xffff0000, v158
	v_lshlrev_b32_e32 v190, 16, v159
	v_and_b32_e32 v191, 0xffff0000, v159
	v_pk_mul_f32 v[184:185], v[184:185], v[48:49] op_sel:[0,1] op_sel_hi:[1,1]
	v_pk_mul_f32 v[186:187], v[186:187], v[48:49] op_sel:[0,1] op_sel_hi:[1,1]
	v_pk_mul_f32 v[188:189], v[188:189], v[48:49] op_sel:[0,1] op_sel_hi:[1,1]
	v_pk_mul_f32 v[190:191], v[190:191], v[48:49] op_sel:[0,1] op_sel_hi:[1,1]
	v_pk_mul_f32 v[184:185], v[184:185], v[8:9]
	v_pk_mul_f32 v[186:187], v[186:187], v[10:11]
	v_pk_mul_f32 v[188:189], v[188:189], v[12:13]
	v_pk_mul_f32 v[190:191], v[190:191], v[14:15]
	v_cvt_pk_bf16_f32 v172, v184, v185
	v_cvt_pk_bf16_f32 v173, v186, v187
	v_cvt_pk_bf16_f32 v174, v188, v189
	v_cvt_pk_bf16_f32 v175, v190, v191
	global_store_dwordx4 v50, v[172:175], s[26:27] offset:1024
	v_lshlrev_b32_e32 v184, 16, v160
	v_and_b32_e32 v185, 0xffff0000, v160
	v_lshlrev_b32_e32 v186, 16, v161
	v_and_b32_e32 v187, 0xffff0000, v161
	v_lshlrev_b32_e32 v188, 16, v162
	v_and_b32_e32 v189, 0xffff0000, v162
	v_lshlrev_b32_e32 v190, 16, v163
	v_and_b32_e32 v191, 0xffff0000, v163
	v_pk_mul_f32 v[184:185], v[184:185], v[48:49] op_sel:[0,1] op_sel_hi:[1,1]
	v_pk_mul_f32 v[186:187], v[186:187], v[48:49] op_sel:[0,1] op_sel_hi:[1,1]
	v_pk_mul_f32 v[188:189], v[188:189], v[48:49] op_sel:[0,1] op_sel_hi:[1,1]
	v_pk_mul_f32 v[190:191], v[190:191], v[48:49] op_sel:[0,1] op_sel_hi:[1,1]
	v_pk_mul_f32 v[184:185], v[184:185], v[16:17]
	v_pk_mul_f32 v[186:187], v[186:187], v[18:19]
	v_pk_mul_f32 v[188:189], v[188:189], v[20:21]
	v_pk_mul_f32 v[190:191], v[190:191], v[22:23]
	v_cvt_pk_bf16_f32 v176, v184, v185
	v_cvt_pk_bf16_f32 v177, v186, v187
	v_cvt_pk_bf16_f32 v178, v188, v189
	v_cvt_pk_bf16_f32 v179, v190, v191
	global_store_dwordx4 v50, v[176:179], s[26:27] offset:2048
	v_lshlrev_b32_e32 v184, 16, v164
	v_and_b32_e32 v185, 0xffff0000, v164
	v_lshlrev_b32_e32 v186, 16, v165
	v_and_b32_e32 v187, 0xffff0000, v165
	v_lshlrev_b32_e32 v188, 16, v166
	v_and_b32_e32 v189, 0xffff0000, v166
	v_lshlrev_b32_e32 v190, 16, v167
	v_and_b32_e32 v191, 0xffff0000, v167
	v_pk_mul_f32 v[184:185], v[184:185], v[48:49] op_sel:[0,1] op_sel_hi:[1,1]
	v_pk_mul_f32 v[186:187], v[186:187], v[48:49] op_sel:[0,1] op_sel_hi:[1,1]
	v_pk_mul_f32 v[188:189], v[188:189], v[48:49] op_sel:[0,1] op_sel_hi:[1,1]
	v_pk_mul_f32 v[190:191], v[190:191], v[48:49] op_sel:[0,1] op_sel_hi:[1,1]
	v_pk_mul_f32 v[184:185], v[184:185], v[24:25]
	v_pk_mul_f32 v[186:187], v[186:187], v[26:27]
	v_pk_mul_f32 v[188:189], v[188:189], v[28:29]
	v_pk_mul_f32 v[190:191], v[190:191], v[30:31]
	v_cvt_pk_bf16_f32 v180, v184, v185
	v_cvt_pk_bf16_f32 v181, v186, v187
	v_cvt_pk_bf16_f32 v182, v188, v189
	v_cvt_pk_bf16_f32 v183, v190, v191
	global_store_dwordx4 v50, v[180:183], s[26:27] offset:3072
	global_load_dwordx4 v[56:59], v50, s[14:15] offset:0
	global_load_dwordx4 v[60:63], v50, s[14:15] offset:1024
	global_load_dwordx4 v[64:67], v50, s[14:15] offset:2048
	global_load_dwordx4 v[68:71], v50, s[14:15] offset:3072
	global_load_dwordx4 v[72:75], v50, s[18:19] offset:0
	global_load_dwordx4 v[76:79], v50, s[18:19] offset:1024
	global_load_dwordx4 v[80:83], v50, s[18:19] offset:2048
	global_load_dwordx4 v[84:87], v50, s[18:19] offset:3072
	global_load_dwordx4 v[88:91], v50, s[20:21] offset:0
	global_load_dwordx4 v[92:95], v50, s[20:21] offset:1024
	global_load_dwordx4 v[96:99], v50, s[20:21] offset:2048
	global_load_dwordx4 v[100:103], v50, s[20:21] offset:3072
	s_mov_b32 s26, s14
	s_mov_b32 s27, s15
	s_add_u32 s14, s14, 0x1000000
	s_addc_u32 s15, s15, 0
	s_add_u32 s18, s18, 0xc00000
	s_addc_u32 s19, s19, 0
	s_add_u32 s20, s20, 0x2500000
	s_addc_u32 s21, s21, 0
	s_waitcnt vmcnt(16)
	v_mov_b32_e32 v44, 0
	v_mov_b32_e32 v45, 0
	v_lshlrev_b32_e32 v184, 16, v104
	v_and_b32_e32 v185, 0xffff0000, v104
	v_lshlrev_b32_e32 v186, 16, v105
	v_and_b32_e32 v187, 0xffff0000, v105
	v_lshlrev_b32_e32 v188, 16, v106
	v_and_b32_e32 v189, 0xffff0000, v106
	v_lshlrev_b32_e32 v190, 16, v107
	v_and_b32_e32 v191, 0xffff0000, v107
	v_lshlrev_b32_e32 v192, 16, v120
	v_and_b32_e32 v193, 0xffff0000, v120
	v_lshlrev_b32_e32 v194, 16, v121
	v_and_b32_e32 v195, 0xffff0000, v121
	v_lshlrev_b32_e32 v196, 16, v122
	v_and_b32_e32 v197, 0xffff0000, v122
	v_lshlrev_b32_e32 v198, 16, v123
	v_and_b32_e32 v199, 0xffff0000, v123
	v_lshlrev_b32_e32 v200, 16, v136
	v_and_b32_e32 v201, 0xffff0000, v136
	v_lshlrev_b32_e32 v202, 16, v137
	v_and_b32_e32 v203, 0xffff0000, v137
	v_lshlrev_b32_e32 v204, 16, v138
	v_and_b32_e32 v205, 0xffff0000, v138
	v_lshlrev_b32_e32 v206, 16, v139
	v_and_b32_e32 v207, 0xffff0000, v139
	v_pk_fma_f32 v[184:185], v[192:193], v[32:33], v[184:185] op_sel:[0,0,0] op_sel_hi:[1,0,1]
	v_pk_fma_f32 v[186:187], v[194:195], v[32:33], v[186:187] op_sel:[0,0,0] op_sel_hi:[1,0,1]
	v_pk_fma_f32 v[188:189], v[196:197], v[32:33], v[188:189] op_sel:[0,0,0] op_sel_hi:[1,0,1]
	v_pk_fma_f32 v[190:191], v[198:199], v[32:33], v[190:191] op_sel:[0,0,0] op_sel_hi:[1,0,1]
	v_pk_mul_f32 v[36:37], v[200:201], v[46:47] op_sel:[0,0] op_sel_hi:[1,0]
	v_pk_mul_f32 v[38:39], v[202:203], v[46:47] op_sel:[0,0] op_sel_hi:[1,0]
	v_pk_mul_f32 v[40:41], v[204:205], v[46:47] op_sel:[0,0] op_sel_hi:[1,0]
	v_pk_mul_f32 v[42:43], v[206:207], v[46:47] op_sel:[0,0] op_sel_hi:[1,0]
	v_exp_f32_e32 v36, v36
	v_exp_f32_e32 v37, v37
	v_exp_f32_e32 v38, v38
	v_exp_f32_e32 v39, v39
	v_exp_f32_e32 v40, v40
	v_exp_f32_e32 v41, v41
	v_exp_f32_e32 v42, v42
; __device__ __forceinline__ float siluf_(float x) { return x * __builtin_amdgcn_rcpf(1.f + __expf(-x)); }
; __device__ __forceinline__ void mix_finalize_ssd(size_t row, bf16_t* MIX, const bf16_t* XBC, const bf16_t* PROJ, const float* d_skip, const float* ssd_norm_w, int lane, bf16_t* ssd_dst) {
;     ...
;         for (int k = 0; k < 4; ++k) { float f[8], xf[8], zf[8]; unpack8(yv[k], f); unpack8(xv[k], xf); unpack8(zv[k], zf);
; #pragma unroll
;             for (int e = 0; e < 8; ++e) { f[e] = (f[e] + dsk[k] * xf[e]) * siluf_(zf[e]); s += f[e] * f[e]; }
;             yv[k] = pack8(f); }
	v_exp_f32_e32 v43, v43
	v_pk_add_f32 v[36:37], v[36:37], v[46:47] op_sel:[0,1] op_sel_hi:[1,1]
	v_pk_add_f32 v[38:39], v[38:39], v[46:47] op_sel:[0,1] op_sel_hi:[1,1]
	v_pk_add_f32 v[40:41], v[40:41], v[46:47] op_sel:[0,1] op_sel_hi:[1,1]
	v_pk_add_f32 v[42:43], v[42:43], v[46:47] op_sel:[0,1] op_sel_hi:[1,1]
	v_rcp_f32_e32 v36, v36
	v_rcp_f32_e32 v37, v37
	v_rcp_f32_e32 v38, v38
	v_rcp_f32_e32 v39, v39
	v_rcp_f32_e32 v40, v40
	v_rcp_f32_e32 v41, v41
	v_rcp_f32_e32 v42, v42
	v_rcp_f32_e32 v43, v43
	v_pk_mul_f32 v[36:37], v[200:201], v[36:37]
	v_pk_mul_f32 v[38:39], v[202:203], v[38:39]
	v_pk_mul_f32 v[40:41], v[204:205], v[40:41]
	v_pk_mul_f32 v[42:43], v[206:207], v[42:43]
	v_pk_mul_f32 v[184:185], v[184:185], v[36:37]
	v_pk_mul_f32 v[186:187], v[186:187], v[38:39]
	v_pk_mul_f32 v[188:189], v[188:189], v[40:41]
	v_pk_mul_f32 v[190:191], v[190:191], v[42:43]
	v_pk_fma_f32 v[44:45], v[184:185], v[184:185], v[44:45]
	v_pk_fma_f32 v[44:45], v[186:187], v[186:187], v[44:45]
	v_pk_fma_f32 v[44:45], v[188:189], v[188:189], v[44:45]
	v_pk_fma_f32 v[44:45], v[190:191], v[190:191], v[44:45]
	v_cvt_pk_bf16_f32 v152, v184, v185
	v_cvt_pk_bf16_f32 v153, v186, v187
	v_cvt_pk_bf16_f32 v154, v188, v189
	v_cvt_pk_bf16_f32 v155, v190, v191
	v_lshlrev_b32_e32 v184, 16, v108
	v_and_b32_e32 v185, 0xffff0000, v108
	v_lshlrev_b32_e32 v186, 16, v109
	v_and_b32_e32 v187, 0xffff0000, v109
	v_lshlrev_b32_e32 v188, 16, v110
	v_and_b32_e32 v189, 0xffff0000, v110
	v_lshlrev_b32_e32 v190, 16, v111
	v_and_b32_e32 v191, 0xffff0000, v111
	v_lshlrev_b32_e32 v192, 16, v124
	v_and_b32_e32 v193, 0xffff0000, v124
	v_lshlrev_b32_e32 v194, 16, v125
	v_and_b32_e32 v195, 0xffff0000, v125
	v_lshlrev_b32_e32 v196, 16, v126
	v_and_b32_e32 v197, 0xffff0000, v126
	v_lshlrev_b32_e32 v198, 16, v127
	v_and_b32_e32 v199, 0xffff0000, v127
	v_lshlrev_b32_e32 v200, 16, v140
	v_and_b32_e32 v201, 0xffff0000, v140
	v_lshlrev_b32_e32 v202, 16, v141
	v_and_b32_e32 v203, 0xffff0000, v141
	v_lshlrev_b32_e32 v204, 16, v142
	v_and_b32_e32 v205, 0xffff0000, v142
	v_lshlrev_b32_e32 v206, 16, v143
	v_and_b32_e32 v207, 0xffff0000, v143
	v_pk_fma_f32 v[184:185], v[192:193], v[32:33], v[184:185] op_sel:[0,1,0] op_sel_hi:[1,1,1]
	v_pk_fma_f32 v[186:187], v[194:195], v[32:33], v[186:187] op_sel:[0,1,0] op_sel_hi:[1,1,1]
	v_pk_fma_f32 v[188:189], v[196:197], v[32:33], v[188:189] op_sel:[0,1,0] op_sel_hi:[1,1,1]
	v_pk_fma_f32 v[190:191], v[198:199], v[32:33], v[190:191] op_sel:[0,1,0] op_sel_hi:[1,1,1]
	v_pk_mul_f32 v[36:37], v[200:201], v[46:47] op_sel:[0,0] op_sel_hi:[1,0]
	v_pk_mul_f32 v[38:39], v[202:203], v[46:47] op_sel:[0,0] op_sel_hi:[1,0]
	v_pk_mul_f32 v[40:41], v[204:205], v[46:47] op_sel:[0,0] op_sel_hi:[1,0]
	v_pk_mul_f32 v[42:43], v[206:207], v[46:47] op_sel:[0,0] op_sel_hi:[1,0]
	v_exp_f32_e32 v36, v36
	v_exp_f32_e32 v37, v37
	v_exp_f32_e32 v38, v38
	v_exp_f32_e32 v39, v39
	v_exp_f32_e32 v40, v40
	v_exp_f32_e32 v41, v41
	v_exp_f32_e32 v42, v42
	v_exp_f32_e32 v43, v43
	v_pk_add_f32 v[36:37], v[36:37], v[46:47] op_sel:[0,1] op_sel_hi:[1,1]
	v_pk_add_f32 v[38:39], v[38:39], v[46:47] op_sel:[0,1] op_sel_hi:[1,1]
	v_pk_add_f32 v[40:41], v[40:41], v[46:47] op_sel:[0,1] op_sel_hi:[1,1]
	v_pk_add_f32 v[42:43], v[42:43], v[46:47] op_sel:[0,1] op_sel_hi:[1,1]
	v_rcp_f32_e32 v36, v36
	v_rcp_f32_e32 v37, v37
	v_rcp_f32_e32 v38, v38
	v_rcp_f32_e32 v39, v39
	v_rcp_f32_e32 v40, v40
	v_rcp_f32_e32 v41, v41
	v_rcp_f32_e32 v42, v42
	v_rcp_f32_e32 v43, v43
	v_pk_mul_f32 v[36:37], v[200:201], v[36:37]
	v_pk_mul_f32 v[38:39], v[202:203], v[38:39]
	v_pk_mul_f32 v[40:41], v[204:205], v[40:41]
	v_pk_mul_f32 v[42:43], v[206:207], v[42:43]
	v_pk_mul_f32 v[184:185], v[184:185], v[36:37]
	v_pk_mul_f32 v[186:187], v[186:187], v[38:39]
	v_pk_mul_f32 v[188:189], v[188:189], v[40:41]
	v_pk_mul_f32 v[190:191], v[190:191], v[42:43]
	v_pk_fma_f32 v[44:45], v[184:185], v[184:185], v[44:45]
	v_pk_fma_f32 v[44:45], v[186:187], v[186:187], v[44:45]
	v_pk_fma_f32 v[44:45], v[188:189], v[188:189], v[44:45]
	v_pk_fma_f32 v[44:45], v[190:191], v[190:191], v[44:45]
	v_cvt_pk_bf16_f32 v156, v184, v185
	v_cvt_pk_bf16_f32 v157, v186, v187
	v_cvt_pk_bf16_f32 v158, v188, v189
	v_cvt_pk_bf16_f32 v159, v190, v191
	v_lshlrev_b32_e32 v184, 16, v112
	v_and_b32_e32 v185, 0xffff0000, v112
	v_lshlrev_b32_e32 v186, 16, v113
	v_and_b32_e32 v187, 0xffff0000, v113
	v_lshlrev_b32_e32 v188, 16, v114
	v_and_b32_e32 v189, 0xffff0000, v114
	v_lshlrev_b32_e32 v190, 16, v115
	v_and_b32_e32 v191, 0xffff0000, v115
	v_lshlrev_b32_e32 v192, 16, v128
	v_and_b32_e32 v193, 0xffff0000, v128
	v_lshlrev_b32_e32 v194, 16, v129
	v_and_b32_e32 v195, 0xffff0000, v129
	v_lshlrev_b32_e32 v196, 16, v130
	v_and_b32_e32 v197, 0xffff0000, v130
	v_lshlrev_b32_e32 v198, 16, v131
	v_and_b32_e32 v199, 0xffff0000, v131
	v_lshlrev_b32_e32 v200, 16, v144
	v_and_b32_e32 v201, 0xffff0000, v144
	v_lshlrev_b32_e32 v202, 16, v145
	v_and_b32_e32 v203, 0xffff0000, v145
	v_lshlrev_b32_e32 v204, 16, v146
	v_and_b32_e32 v205, 0xffff0000, v146
	v_lshlrev_b32_e32 v206, 16, v147
	v_and_b32_e32 v207, 0xffff0000, v147
	v_pk_fma_f32 v[184:185], v[192:193], v[34:35], v[184:185] op_sel:[0,0,0] op_sel_hi:[1,0,1]
	v_pk_fma_f32 v[186:187], v[194:195], v[34:35], v[186:187] op_sel:[0,0,0] op_sel_hi:[1,0,1]
	v_pk_fma_f32 v[188:189], v[196:197], v[34:35], v[188:189] op_sel:[0,0,0] op_sel_hi:[1,0,1]
	v_pk_fma_f32 v[190:191], v[198:199], v[34:35], v[190:191] op_sel:[0,0,0] op_sel_hi:[1,0,1]
	v_pk_mul_f32 v[36:37], v[200:201], v[46:47] op_sel:[0,0] op_sel_hi:[1,0]
	v_pk_mul_f32 v[38:39], v[202:203], v[46:47] op_sel:[0,0] op_sel_hi:[1,0]
	v_pk_mul_f32 v[40:41], v[204:205], v[46:47] op_sel:[0,0] op_sel_hi:[1,0]
; __device__ __forceinline__ float siluf_(float x) { return x * __builtin_amdgcn_rcpf(1.f + __expf(-x)); }
; __device__ __forceinline__ float wave_sum(float v) {
; #pragma unroll
;     for (int o = 1; o < 64; o <<= 1) v += __shfl_xor(v, o);
;     return v;
; __device__ __forceinline__ void mix_finalize_ssd(size_t row, bf16_t* MIX, const bf16_t* XBC, const bf16_t* PROJ, const float* d_skip, const float* ssd_norm_w, int lane, bf16_t* ssd_dst) {
;     ...
;         for (int k = 0; k < 4; ++k) { float f[8], xf[8], zf[8]; unpack8(yv[k], f); unpack8(xv[k], xf); unpack8(zv[k], zf);
; #pragma unroll
;             for (int e = 0; e < 8; ++e) { f[e] = (f[e] + dsk[k] * xf[e]) * siluf_(zf[e]); s += f[e] * f[e]; }
;             yv[k] = pack8(f); }
;         const float r = rsqrtf(wave_sum(s) * (1.f / DM) + EPS);
; #pragma unroll 1
;         for (int k = 0; k < 4; ++k) { const int c = (k * 64 + lane) * 8;
;             const f32x4 w0 = *(const f32x4*)(ssd_norm_w + c), w1 = *(const f32x4*)(ssd_norm_w + c + 4);
;             const u32x4 yk = (k == 0) ? yv[0] : (k == 1) ? yv[1] : (k == 2) ? yv[2] : yv[3];
;             float f[8]; unpack8(yk, f);
;             float o[8]; o[0] = f[0] * r * w0.x; o[1] = f[1] * r * w0.y; o[2] = f[2] * r * w0.z; o[3] = f[3] * r * w0.w;
;             o[4] = f[4] * r * w1.x; o[5] = f[5] * r * w1.y; o[6] = f[6] * r * w1.z; o[7] = f[7] * r * w1.w;
;             *(u32x4*)(ssd_dst + c) = pack8(o); }
	v_pk_mul_f32 v[42:43], v[206:207], v[46:47] op_sel:[0,0] op_sel_hi:[1,0]
	v_exp_f32_e32 v36, v36
	v_exp_f32_e32 v37, v37
	v_exp_f32_e32 v38, v38
	v_exp_f32_e32 v39, v39
	v_exp_f32_e32 v40, v40
	v_exp_f32_e32 v41, v41
	v_exp_f32_e32 v42, v42
	v_exp_f32_e32 v43, v43
	v_pk_add_f32 v[36:37], v[36:37], v[46:47] op_sel:[0,1] op_sel_hi:[1,1]
	v_pk_add_f32 v[38:39], v[38:39], v[46:47] op_sel:[0,1] op_sel_hi:[1,1]
	v_pk_add_f32 v[40:41], v[40:41], v[46:47] op_sel:[0,1] op_sel_hi:[1,1]
	v_pk_add_f32 v[42:43], v[42:43], v[46:47] op_sel:[0,1] op_sel_hi:[1,1]
	v_rcp_f32_e32 v36, v36
	v_rcp_f32_e32 v37, v37
	v_rcp_f32_e32 v38, v38
	v_rcp_f32_e32 v39, v39
	v_rcp_f32_e32 v40, v40
	v_rcp_f32_e32 v41, v41
	v_rcp_f32_e32 v42, v42
	v_rcp_f32_e32 v43, v43
	v_pk_mul_f32 v[36:37], v[200:201], v[36:37]
	v_pk_mul_f32 v[38:39], v[202:203], v[38:39]
	v_pk_mul_f32 v[40:41], v[204:205], v[40:41]
	v_pk_mul_f32 v[42:43], v[206:207], v[42:43]
	v_pk_mul_f32 v[184:185], v[184:185], v[36:37]
	v_pk_mul_f32 v[186:187], v[186:187], v[38:39]
	v_pk_mul_f32 v[188:189], v[188:189], v[40:41]
	v_pk_mul_f32 v[190:191], v[190:191], v[42:43]
	v_pk_fma_f32 v[44:45], v[184:185], v[184:185], v[44:45]
	v_pk_fma_f32 v[44:45], v[186:187], v[186:187], v[44:45]
	v_pk_fma_f32 v[44:45], v[188:189], v[188:189], v[44:45]
	v_pk_fma_f32 v[44:45], v[190:191], v[190:191], v[44:45]
	v_cvt_pk_bf16_f32 v160, v184, v185
	v_cvt_pk_bf16_f32 v161, v186, v187
	v_cvt_pk_bf16_f32 v162, v188, v189
	v_cvt_pk_bf16_f32 v163, v190, v191
	v_lshlrev_b32_e32 v184, 16, v116
	v_and_b32_e32 v185, 0xffff0000, v116
	v_lshlrev_b32_e32 v186, 16, v117
	v_and_b32_e32 v187, 0xffff0000, v117
	v_lshlrev_b32_e32 v188, 16, v118
	v_and_b32_e32 v189, 0xffff0000, v118
	v_lshlrev_b32_e32 v190, 16, v119
	v_and_b32_e32 v191, 0xffff0000, v119
	v_lshlrev_b32_e32 v192, 16, v132
	v_and_b32_e32 v193, 0xffff0000, v132
	v_lshlrev_b32_e32 v194, 16, v133
	v_and_b32_e32 v195, 0xffff0000, v133
	v_lshlrev_b32_e32 v196, 16, v134
	v_and_b32_e32 v197, 0xffff0000, v134
	v_lshlrev_b32_e32 v198, 16, v135
	v_and_b32_e32 v199, 0xffff0000, v135
	v_lshlrev_b32_e32 v200, 16, v148
	v_and_b32_e32 v201, 0xffff0000, v148
	v_lshlrev_b32_e32 v202, 16, v149
	v_and_b32_e32 v203, 0xffff0000, v149
	v_lshlrev_b32_e32 v204, 16, v150
	v_and_b32_e32 v205, 0xffff0000, v150
	v_lshlrev_b32_e32 v206, 16, v151
	v_and_b32_e32 v207, 0xffff0000, v151
	v_pk_fma_f32 v[184:185], v[192:193], v[34:35], v[184:185] op_sel:[0,1,0] op_sel_hi:[1,1,1]
	v_pk_fma_f32 v[186:187], v[194:195], v[34:35], v[186:187] op_sel:[0,1,0] op_sel_hi:[1,1,1]
	v_pk_fma_f32 v[188:189], v[196:197], v[34:35], v[188:189] op_sel:[0,1,0] op_sel_hi:[1,1,1]
	v_pk_fma_f32 v[190:191], v[198:199], v[34:35], v[190:191] op_sel:[0,1,0] op_sel_hi:[1,1,1]
	v_pk_mul_f32 v[36:37], v[200:201], v[46:47] op_sel:[0,0] op_sel_hi:[1,0]
	v_pk_mul_f32 v[38:39], v[202:203], v[46:47] op_sel:[0,0] op_sel_hi:[1,0]
	v_pk_mul_f32 v[40:41], v[204:205], v[46:47] op_sel:[0,0] op_sel_hi:[1,0]
	v_pk_mul_f32 v[42:43], v[206:207], v[46:47] op_sel:[0,0] op_sel_hi:[1,0]
	v_exp_f32_e32 v36, v36
	v_exp_f32_e32 v37, v37
	v_exp_f32_e32 v38, v38
	v_exp_f32_e32 v39, v39
	v_exp_f32_e32 v40, v40
	v_exp_f32_e32 v41, v41
	v_exp_f32_e32 v42, v42
	v_exp_f32_e32 v43, v43
	v_pk_add_f32 v[36:37], v[36:37], v[46:47] op_sel:[0,1] op_sel_hi:[1,1]
	v_pk_add_f32 v[38:39], v[38:39], v[46:47] op_sel:[0,1] op_sel_hi:[1,1]
	v_pk_add_f32 v[40:41], v[40:41], v[46:47] op_sel:[0,1] op_sel_hi:[1,1]
	v_pk_add_f32 v[42:43], v[42:43], v[46:47] op_sel:[0,1] op_sel_hi:[1,1]
	v_rcp_f32_e32 v36, v36
	v_rcp_f32_e32 v37, v37
	v_rcp_f32_e32 v38, v38
	v_rcp_f32_e32 v39, v39
	v_rcp_f32_e32 v40, v40
	v_rcp_f32_e32 v41, v41
	v_rcp_f32_e32 v42, v42
	v_rcp_f32_e32 v43, v43
	v_pk_mul_f32 v[36:37], v[200:201], v[36:37]
	v_pk_mul_f32 v[38:39], v[202:203], v[38:39]
	v_pk_mul_f32 v[40:41], v[204:205], v[40:41]
	v_pk_mul_f32 v[42:43], v[206:207], v[42:43]
	v_pk_mul_f32 v[184:185], v[184:185], v[36:37]
	v_pk_mul_f32 v[186:187], v[186:187], v[38:39]
	v_pk_mul_f32 v[188:189], v[188:189], v[40:41]
	v_pk_mul_f32 v[190:191], v[190:191], v[42:43]
	v_pk_fma_f32 v[44:45], v[184:185], v[184:185], v[44:45]
	v_pk_fma_f32 v[44:45], v[186:187], v[186:187], v[44:45]
	v_pk_fma_f32 v[44:45], v[188:189], v[188:189], v[44:45]
	v_pk_fma_f32 v[44:45], v[190:191], v[190:191], v[44:45]
	v_cvt_pk_bf16_f32 v164, v184, v185
	v_cvt_pk_bf16_f32 v165, v186, v187
	v_cvt_pk_bf16_f32 v166, v188, v189
	v_cvt_pk_bf16_f32 v167, v190, v191
	v_add_f32_e32 v208, v44, v45
	s_nop 1
	v_add_f32_dpp v209, v208, v208 quad_perm:[1,0,3,2] row_mask:0xf bank_mask:0xf
	s_nop 1
	v_add_f32_dpp v208, v209, v209 quad_perm:[2,3,0,1] row_mask:0xf bank_mask:0xf
	s_nop 1
	v_add_f32_dpp v209, v208, v208 row_half_mirror row_mask:0xf bank_mask:0xf
	s_nop 1
	v_add_f32_dpp v208, v209, v209 row_mirror row_mask:0xf bank_mask:0xf
	s_nop 1
	v_readlane_b32 s10, v208, 0
	v_readlane_b32 s11, v208, 16
	v_readlane_b32 s17, v208, 32
	v_readlane_b32 s24, v208, 48
	s_nop 3
	v_mov_b32_e32 v208, s10
	v_add_f32_e32 v208, s11, v208
	v_add_f32_e32 v208, s17, v208
	v_add_f32_e32 v208, s24, v208
	v_fmamk_f32 v208, v208, 0x3a000000, v48
	v_rsq_f32_e32 v49, v208
	s_nop 0
	v_lshlrev_b32_e32 v184, 16, v152
	v_and_b32_e32 v185, 0xffff0000, v152
	v_lshlrev_b32_e32 v186, 16, v153
	v_and_b32_e32 v187, 0xffff0000, v153
	v_lshlrev_b32_e32 v188, 16, v154
	v_and_b32_e32 v189, 0xffff0000, v154
	v_lshlrev_b32_e32 v190, 16, v155
	v_and_b32_e32 v191, 0xffff0000, v155
	v_pk_mul_f32 v[184:185], v[184:185], v[48:49] op_sel:[0,1] op_sel_hi:[1,1]
	v_pk_mul_f32 v[186:187], v[186:187], v[48:49] op_sel:[0,1] op_sel_hi:[1,1]
	v_pk_mul_f32 v[188:189], v[188:189], v[48:49] op_sel:[0,1] op_sel_hi:[1,1]
; __device__ __forceinline__ float siluf_(float x) { return x * __builtin_amdgcn_rcpf(1.f + __expf(-x)); }
; __device__ __forceinline__ void mix_finalize_ssd(size_t row, bf16_t* MIX, const bf16_t* XBC, const bf16_t* PROJ, const float* d_skip, const float* ssd_norm_w, int lane, bf16_t* ssd_dst) {
;     ...
;         for (int k = 0; k < 4; ++k) { const int c = (k * 64 + lane) * 8;
;             yv[k] = *(const u32x4*)(mp + c); xv[k] = *(const u32x4*)(XBC + row * XBCW + c); zv[k] = *(const u32x4*)(PROJ + row * NPROJ + CZ + c);
;             dsk[k] = d_skip[c >> 6]; }
;         float s = 0.f;
; #pragma unroll
;         for (int k = 0; k < 4; ++k) { float f[8], xf[8], zf[8]; unpack8(yv[k], f); unpack8(xv[k], xf); unpack8(zv[k], zf);
; #pragma unroll
;             for (int e = 0; e < 8; ++e) { f[e] = (f[e] + dsk[k] * xf[e]) * siluf_(zf[e]); s += f[e] * f[e]; }
;             yv[k] = pack8(f); }
;     ...
;         for (int k = 0; k < 4; ++k) { const int c = (k * 64 + lane) * 8;
;             const f32x4 w0 = *(const f32x4*)(ssd_norm_w + c), w1 = *(const f32x4*)(ssd_norm_w + c + 4);
;             const u32x4 yk = (k == 0) ? yv[0] : (k == 1) ? yv[1] : (k == 2) ? yv[2] : yv[3];
;             float f[8]; unpack8(yk, f);
;             float o[8]; o[0] = f[0] * r * w0.x; o[1] = f[1] * r * w0.y; o[2] = f[2] * r * w0.z; o[3] = f[3] * r * w0.w;
;             o[4] = f[4] * r * w1.x; o[5] = f[5] * r * w1.y; o[6] = f[6] * r * w1.z; o[7] = f[7] * r * w1.w;
;             *(u32x4*)(ssd_dst + c) = pack8(o); }
	v_pk_mul_f32 v[190:191], v[190:191], v[48:49] op_sel:[0,1] op_sel_hi:[1,1]
	v_pk_mul_f32 v[184:185], v[184:185], v[0:1]
	v_pk_mul_f32 v[186:187], v[186:187], v[2:3]
	v_pk_mul_f32 v[188:189], v[188:189], v[4:5]
	v_pk_mul_f32 v[190:191], v[190:191], v[6:7]
	v_cvt_pk_bf16_f32 v168, v184, v185
	v_cvt_pk_bf16_f32 v169, v186, v187
	v_cvt_pk_bf16_f32 v170, v188, v189
	v_cvt_pk_bf16_f32 v171, v190, v191
	global_store_dwordx4 v50, v[168:171], s[12:13] offset:0
	v_lshlrev_b32_e32 v184, 16, v156
	v_and_b32_e32 v185, 0xffff0000, v156
	v_lshlrev_b32_e32 v186, 16, v157
	v_and_b32_e32 v187, 0xffff0000, v157
	v_lshlrev_b32_e32 v188, 16, v158
	v_and_b32_e32 v189, 0xffff0000, v158
	v_lshlrev_b32_e32 v190, 16, v159
	v_and_b32_e32 v191, 0xffff0000, v159
	v_pk_mul_f32 v[184:185], v[184:185], v[48:49] op_sel:[0,1] op_sel_hi:[1,1]
	v_pk_mul_f32 v[186:187], v[186:187], v[48:49] op_sel:[0,1] op_sel_hi:[1,1]
	v_pk_mul_f32 v[188:189], v[188:189], v[48:49] op_sel:[0,1] op_sel_hi:[1,1]
	v_pk_mul_f32 v[190:191], v[190:191], v[48:49] op_sel:[0,1] op_sel_hi:[1,1]
	v_pk_mul_f32 v[184:185], v[184:185], v[8:9]
	v_pk_mul_f32 v[186:187], v[186:187], v[10:11]
	v_pk_mul_f32 v[188:189], v[188:189], v[12:13]
	v_pk_mul_f32 v[190:191], v[190:191], v[14:15]
	v_cvt_pk_bf16_f32 v172, v184, v185
	v_cvt_pk_bf16_f32 v173, v186, v187
	v_cvt_pk_bf16_f32 v174, v188, v189
	v_cvt_pk_bf16_f32 v175, v190, v191
	global_store_dwordx4 v50, v[172:175], s[12:13] offset:1024
	v_lshlrev_b32_e32 v184, 16, v160
	v_and_b32_e32 v185, 0xffff0000, v160
	v_lshlrev_b32_e32 v186, 16, v161
	v_and_b32_e32 v187, 0xffff0000, v161
	v_lshlrev_b32_e32 v188, 16, v162
	v_and_b32_e32 v189, 0xffff0000, v162
	v_lshlrev_b32_e32 v190, 16, v163
	v_and_b32_e32 v191, 0xffff0000, v163
	v_pk_mul_f32 v[184:185], v[184:185], v[48:49] op_sel:[0,1] op_sel_hi:[1,1]
	v_pk_mul_f32 v[186:187], v[186:187], v[48:49] op_sel:[0,1] op_sel_hi:[1,1]
	v_pk_mul_f32 v[188:189], v[188:189], v[48:49] op_sel:[0,1] op_sel_hi:[1,1]
	v_pk_mul_f32 v[190:191], v[190:191], v[48:49] op_sel:[0,1] op_sel_hi:[1,1]
	v_pk_mul_f32 v[184:185], v[184:185], v[16:17]
	v_pk_mul_f32 v[186:187], v[186:187], v[18:19]
	v_pk_mul_f32 v[188:189], v[188:189], v[20:21]
	v_pk_mul_f32 v[190:191], v[190:191], v[22:23]
	v_cvt_pk_bf16_f32 v176, v184, v185
	v_cvt_pk_bf16_f32 v177, v186, v187
	v_cvt_pk_bf16_f32 v178, v188, v189
	v_cvt_pk_bf16_f32 v179, v190, v191
	global_store_dwordx4 v50, v[176:179], s[12:13] offset:2048
	v_lshlrev_b32_e32 v184, 16, v164
	v_and_b32_e32 v185, 0xffff0000, v164
	v_lshlrev_b32_e32 v186, 16, v165
	v_and_b32_e32 v187, 0xffff0000, v165
	v_lshlrev_b32_e32 v188, 16, v166
	v_and_b32_e32 v189, 0xffff0000, v166
	v_lshlrev_b32_e32 v190, 16, v167
	v_and_b32_e32 v191, 0xffff0000, v167
	v_pk_mul_f32 v[184:185], v[184:185], v[48:49] op_sel:[0,1] op_sel_hi:[1,1]
	v_pk_mul_f32 v[186:187], v[186:187], v[48:49] op_sel:[0,1] op_sel_hi:[1,1]
	v_pk_mul_f32 v[188:189], v[188:189], v[48:49] op_sel:[0,1] op_sel_hi:[1,1]
	v_pk_mul_f32 v[190:191], v[190:191], v[48:49] op_sel:[0,1] op_sel_hi:[1,1]
	v_pk_mul_f32 v[184:185], v[184:185], v[24:25]
	v_pk_mul_f32 v[186:187], v[186:187], v[26:27]
	v_pk_mul_f32 v[188:189], v[188:189], v[28:29]
	v_pk_mul_f32 v[190:191], v[190:191], v[30:31]
	v_cvt_pk_bf16_f32 v180, v184, v185
	v_cvt_pk_bf16_f32 v181, v186, v187
	v_cvt_pk_bf16_f32 v182, v188, v189
	v_cvt_pk_bf16_f32 v183, v190, v191
	global_store_dwordx4 v50, v[180:183], s[12:13] offset:3072
	global_load_dwordx4 v[104:107], v50, s[14:15] offset:0
	global_load_dwordx4 v[108:111], v50, s[14:15] offset:1024
	global_load_dwordx4 v[112:115], v50, s[14:15] offset:2048
	global_load_dwordx4 v[116:119], v50, s[14:15] offset:3072
	global_load_dwordx4 v[120:123], v50, s[18:19] offset:0
	global_load_dwordx4 v[124:127], v50, s[18:19] offset:1024
	global_load_dwordx4 v[128:131], v50, s[18:19] offset:2048
	global_load_dwordx4 v[132:135], v50, s[18:19] offset:3072
	global_load_dwordx4 v[136:139], v50, s[20:21] offset:0
	global_load_dwordx4 v[140:143], v50, s[20:21] offset:1024
	global_load_dwordx4 v[144:147], v50, s[20:21] offset:2048
	global_load_dwordx4 v[148:151], v50, s[20:21] offset:3072
	s_mov_b32 s12, s14
	s_mov_b32 s13, s15
	s_waitcnt vmcnt(16)
	v_mov_b32_e32 v44, 0
	v_mov_b32_e32 v45, 0
	v_lshlrev_b32_e32 v184, 16, v56
	v_and_b32_e32 v185, 0xffff0000, v56
	v_lshlrev_b32_e32 v186, 16, v57
	v_and_b32_e32 v187, 0xffff0000, v57
	v_lshlrev_b32_e32 v188, 16, v58
	v_and_b32_e32 v189, 0xffff0000, v58
	v_lshlrev_b32_e32 v190, 16, v59
	v_and_b32_e32 v191, 0xffff0000, v59
	v_lshlrev_b32_e32 v192, 16, v72
	v_and_b32_e32 v193, 0xffff0000, v72
	v_lshlrev_b32_e32 v194, 16, v73
	v_and_b32_e32 v195, 0xffff0000, v73
	v_lshlrev_b32_e32 v196, 16, v74
	v_and_b32_e32 v197, 0xffff0000, v74
	v_lshlrev_b32_e32 v198, 16, v75
	v_and_b32_e32 v199, 0xffff0000, v75
	v_lshlrev_b32_e32 v200, 16, v88
	v_and_b32_e32 v201, 0xffff0000, v88
	v_lshlrev_b32_e32 v202, 16, v89
	v_and_b32_e32 v203, 0xffff0000, v89
	v_lshlrev_b32_e32 v204, 16, v90
	v_and_b32_e32 v205, 0xffff0000, v90
	v_lshlrev_b32_e32 v206, 16, v91
	v_and_b32_e32 v207, 0xffff0000, v91
	v_pk_fma_f32 v[184:185], v[192:193], v[32:33], v[184:185] op_sel:[0,0,0] op_sel_hi:[1,0,1]
	v_pk_fma_f32 v[186:187], v[194:195], v[32:33], v[186:187] op_sel:[0,0,0] op_sel_hi:[1,0,1]
	v_pk_fma_f32 v[188:189], v[196:197], v[32:33], v[188:189] op_sel:[0,0,0] op_sel_hi:[1,0,1]
	v_pk_fma_f32 v[190:191], v[198:199], v[32:33], v[190:191] op_sel:[0,0,0] op_sel_hi:[1,0,1]
	v_pk_mul_f32 v[36:37], v[200:201], v[46:47] op_sel:[0,0] op_sel_hi:[1,0]
	v_pk_mul_f32 v[38:39], v[202:203], v[46:47] op_sel:[0,0] op_sel_hi:[1,0]
	v_pk_mul_f32 v[40:41], v[204:205], v[46:47] op_sel:[0,0] op_sel_hi:[1,0]
; __device__ __forceinline__ float siluf_(float x) { return x * __builtin_amdgcn_rcpf(1.f + __expf(-x)); }
; __device__ __forceinline__ void mix_finalize_ssd(size_t row, bf16_t* MIX, const bf16_t* XBC, const bf16_t* PROJ, const float* d_skip, const float* ssd_norm_w, int lane, bf16_t* ssd_dst) {
;     ...
;         for (int k = 0; k < 4; ++k) { float f[8], xf[8], zf[8]; unpack8(yv[k], f); unpack8(xv[k], xf); unpack8(zv[k], zf);
; #pragma unroll
;             for (int e = 0; e < 8; ++e) { f[e] = (f[e] + dsk[k] * xf[e]) * siluf_(zf[e]); s += f[e] * f[e]; }
;             yv[k] = pack8(f); }
	v_pk_mul_f32 v[42:43], v[206:207], v[46:47] op_sel:[0,0] op_sel_hi:[1,0]
	v_exp_f32_e32 v36, v36
	v_exp_f32_e32 v37, v37
	v_exp_f32_e32 v38, v38
	v_exp_f32_e32 v39, v39
	v_exp_f32_e32 v40, v40
	v_exp_f32_e32 v41, v41
	v_exp_f32_e32 v42, v42
	v_exp_f32_e32 v43, v43
	v_pk_add_f32 v[36:37], v[36:37], v[46:47] op_sel:[0,1] op_sel_hi:[1,1]
	v_pk_add_f32 v[38:39], v[38:39], v[46:47] op_sel:[0,1] op_sel_hi:[1,1]
	v_pk_add_f32 v[40:41], v[40:41], v[46:47] op_sel:[0,1] op_sel_hi:[1,1]
	v_pk_add_f32 v[42:43], v[42:43], v[46:47] op_sel:[0,1] op_sel_hi:[1,1]
	v_rcp_f32_e32 v36, v36
	v_rcp_f32_e32 v37, v37
	v_rcp_f32_e32 v38, v38
	v_rcp_f32_e32 v39, v39
	v_rcp_f32_e32 v40, v40
	v_rcp_f32_e32 v41, v41
	v_rcp_f32_e32 v42, v42
	v_rcp_f32_e32 v43, v43
	v_pk_mul_f32 v[36:37], v[200:201], v[36:37]
	v_pk_mul_f32 v[38:39], v[202:203], v[38:39]
	v_pk_mul_f32 v[40:41], v[204:205], v[40:41]
	v_pk_mul_f32 v[42:43], v[206:207], v[42:43]
	v_pk_mul_f32 v[184:185], v[184:185], v[36:37]
	v_pk_mul_f32 v[186:187], v[186:187], v[38:39]
	v_pk_mul_f32 v[188:189], v[188:189], v[40:41]
	v_pk_mul_f32 v[190:191], v[190:191], v[42:43]
	v_pk_fma_f32 v[44:45], v[184:185], v[184:185], v[44:45]
	v_pk_fma_f32 v[44:45], v[186:187], v[186:187], v[44:45]
	v_pk_fma_f32 v[44:45], v[188:189], v[188:189], v[44:45]
	v_pk_fma_f32 v[44:45], v[190:191], v[190:191], v[44:45]
	v_cvt_pk_bf16_f32 v152, v184, v185
	v_cvt_pk_bf16_f32 v153, v186, v187
	v_cvt_pk_bf16_f32 v154, v188, v189
	v_cvt_pk_bf16_f32 v155, v190, v191
	v_lshlrev_b32_e32 v184, 16, v60
	v_and_b32_e32 v185, 0xffff0000, v60
	v_lshlrev_b32_e32 v186, 16, v61
	v_and_b32_e32 v187, 0xffff0000, v61
	v_lshlrev_b32_e32 v188, 16, v62
	v_and_b32_e32 v189, 0xffff0000, v62
	v_lshlrev_b32_e32 v190, 16, v63
	v_and_b32_e32 v191, 0xffff0000, v63
	v_lshlrev_b32_e32 v192, 16, v76
	v_and_b32_e32 v193, 0xffff0000, v76
	v_lshlrev_b32_e32 v194, 16, v77
	v_and_b32_e32 v195, 0xffff0000, v77
	v_lshlrev_b32_e32 v196, 16, v78
	v_and_b32_e32 v197, 0xffff0000, v78
	v_lshlrev_b32_e32 v198, 16, v79
	v_and_b32_e32 v199, 0xffff0000, v79
	v_lshlrev_b32_e32 v200, 16, v92
	v_and_b32_e32 v201, 0xffff0000, v92
	v_lshlrev_b32_e32 v202, 16, v93
	v_and_b32_e32 v203, 0xffff0000, v93
	v_lshlrev_b32_e32 v204, 16, v94
	v_and_b32_e32 v205, 0xffff0000, v94
	v_lshlrev_b32_e32 v206, 16, v95
	v_and_b32_e32 v207, 0xffff0000, v95
	v_pk_fma_f32 v[184:185], v[192:193], v[32:33], v[184:185] op_sel:[0,1,0] op_sel_hi:[1,1,1]
	v_pk_fma_f32 v[186:187], v[194:195], v[32:33], v[186:187] op_sel:[0,1,0] op_sel_hi:[1,1,1]
	v_pk_fma_f32 v[188:189], v[196:197], v[32:33], v[188:189] op_sel:[0,1,0] op_sel_hi:[1,1,1]
	v_pk_fma_f32 v[190:191], v[198:199], v[32:33], v[190:191] op_sel:[0,1,0] op_sel_hi:[1,1,1]
	v_pk_mul_f32 v[36:37], v[200:201], v[46:47] op_sel:[0,0] op_sel_hi:[1,0]
	v_pk_mul_f32 v[38:39], v[202:203], v[46:47] op_sel:[0,0] op_sel_hi:[1,0]
	v_pk_mul_f32 v[40:41], v[204:205], v[46:47] op_sel:[0,0] op_sel_hi:[1,0]
	v_pk_mul_f32 v[42:43], v[206:207], v[46:47] op_sel:[0,0] op_sel_hi:[1,0]
	v_exp_f32_e32 v36, v36
	v_exp_f32_e32 v37, v37
	v_exp_f32_e32 v38, v38
	v_exp_f32_e32 v39, v39
	v_exp_f32_e32 v40, v40
	v_exp_f32_e32 v41, v41
	v_exp_f32_e32 v42, v42
	v_exp_f32_e32 v43, v43
	v_pk_add_f32 v[36:37], v[36:37], v[46:47] op_sel:[0,1] op_sel_hi:[1,1]
	v_pk_add_f32 v[38:39], v[38:39], v[46:47] op_sel:[0,1] op_sel_hi:[1,1]
	v_pk_add_f32 v[40:41], v[40:41], v[46:47] op_sel:[0,1] op_sel_hi:[1,1]
	v_pk_add_f32 v[42:43], v[42:43], v[46:47] op_sel:[0,1] op_sel_hi:[1,1]
	v_rcp_f32_e32 v36, v36
	v_rcp_f32_e32 v37, v37
	v_rcp_f32_e32 v38, v38
	v_rcp_f32_e32 v39, v39
	v_rcp_f32_e32 v40, v40
	v_rcp_f32_e32 v41, v41
	v_rcp_f32_e32 v42, v42
	v_rcp_f32_e32 v43, v43
	v_pk_mul_f32 v[36:37], v[200:201], v[36:37]
	v_pk_mul_f32 v[38:39], v[202:203], v[38:39]
	v_pk_mul_f32 v[40:41], v[204:205], v[40:41]
	v_pk_mul_f32 v[42:43], v[206:207], v[42:43]
	v_pk_mul_f32 v[184:185], v[184:185], v[36:37]
	v_pk_mul_f32 v[186:187], v[186:187], v[38:39]
	v_pk_mul_f32 v[188:189], v[188:189], v[40:41]
	v_pk_mul_f32 v[190:191], v[190:191], v[42:43]
	v_pk_fma_f32 v[44:45], v[184:185], v[184:185], v[44:45]
	v_pk_fma_f32 v[44:45], v[186:187], v[186:187], v[44:45]
	v_pk_fma_f32 v[44:45], v[188:189], v[188:189], v[44:45]
	v_pk_fma_f32 v[44:45], v[190:191], v[190:191], v[44:45]
	v_cvt_pk_bf16_f32 v156, v184, v185
	v_cvt_pk_bf16_f32 v157, v186, v187
	v_cvt_pk_bf16_f32 v158, v188, v189
	v_cvt_pk_bf16_f32 v159, v190, v191
	v_lshlrev_b32_e32 v184, 16, v64
	v_and_b32_e32 v185, 0xffff0000, v64
	v_lshlrev_b32_e32 v186, 16, v65
	v_and_b32_e32 v187, 0xffff0000, v65
	v_lshlrev_b32_e32 v188, 16, v66
	v_and_b32_e32 v189, 0xffff0000, v66
	v_lshlrev_b32_e32 v190, 16, v67
	v_and_b32_e32 v191, 0xffff0000, v67
	v_lshlrev_b32_e32 v192, 16, v80
	v_and_b32_e32 v193, 0xffff0000, v80
	v_lshlrev_b32_e32 v194, 16, v81
	v_and_b32_e32 v195, 0xffff0000, v81
	v_lshlrev_b32_e32 v196, 16, v82
	v_and_b32_e32 v197, 0xffff0000, v82
	v_lshlrev_b32_e32 v198, 16, v83
	v_and_b32_e32 v199, 0xffff0000, v83
	v_lshlrev_b32_e32 v200, 16, v96
	v_and_b32_e32 v201, 0xffff0000, v96
	v_lshlrev_b32_e32 v202, 16, v97
	v_and_b32_e32 v203, 0xffff0000, v97
	v_lshlrev_b32_e32 v204, 16, v98
	v_and_b32_e32 v205, 0xffff0000, v98
	v_lshlrev_b32_e32 v206, 16, v99
	v_and_b32_e32 v207, 0xffff0000, v99
	v_pk_fma_f32 v[184:185], v[192:193], v[34:35], v[184:185] op_sel:[0,0,0] op_sel_hi:[1,0,1]
	v_pk_fma_f32 v[186:187], v[194:195], v[34:35], v[186:187] op_sel:[0,0,0] op_sel_hi:[1,0,1]
	v_pk_fma_f32 v[188:189], v[196:197], v[34:35], v[188:189] op_sel:[0,0,0] op_sel_hi:[1,0,1]
	v_pk_fma_f32 v[190:191], v[198:199], v[34:35], v[190:191] op_sel:[0,0,0] op_sel_hi:[1,0,1]
; __device__ __forceinline__ float siluf_(float x) { return x * __builtin_amdgcn_rcpf(1.f + __expf(-x)); }
; __device__ __forceinline__ float wave_sum(float v) {
; #pragma unroll
;     for (int o = 1; o < 64; o <<= 1) v += __shfl_xor(v, o);
;     return v;
; __device__ __forceinline__ void mix_finalize_ssd(size_t row, bf16_t* MIX, const bf16_t* XBC, const bf16_t* PROJ, const float* d_skip, const float* ssd_norm_w, int lane, bf16_t* ssd_dst) {
;     ...
;         for (int k = 0; k < 4; ++k) { float f[8], xf[8], zf[8]; unpack8(yv[k], f); unpack8(xv[k], xf); unpack8(zv[k], zf);
; #pragma unroll
;             for (int e = 0; e < 8; ++e) { f[e] = (f[e] + dsk[k] * xf[e]) * siluf_(zf[e]); s += f[e] * f[e]; }
;             yv[k] = pack8(f); }
;         const float r = rsqrtf(wave_sum(s) * (1.f / DM) + EPS);
; #pragma unroll 1
;         for (int k = 0; k < 4; ++k) { const int c = (k * 64 + lane) * 8;
;             const f32x4 w0 = *(const f32x4*)(ssd_norm_w + c), w1 = *(const f32x4*)(ssd_norm_w + c + 4);
;             const u32x4 yk = (k == 0) ? yv[0] : (k == 1) ? yv[1] : (k == 2) ? yv[2] : yv[3];
;             float f[8]; unpack8(yk, f);
;             float o[8]; o[0] = f[0] * r * w0.x; o[1] = f[1] * r * w0.y; o[2] = f[2] * r * w0.z; o[3] = f[3] * r * w0.w;
;             o[4] = f[4] * r * w1.x; o[5] = f[5] * r * w1.y; o[6] = f[6] * r * w1.z; o[7] = f[7] * r * w1.w;
;             *(u32x4*)(ssd_dst + c) = pack8(o); }
	v_pk_mul_f32 v[36:37], v[200:201], v[46:47] op_sel:[0,0] op_sel_hi:[1,0]
	v_pk_mul_f32 v[38:39], v[202:203], v[46:47] op_sel:[0,0] op_sel_hi:[1,0]
	v_pk_mul_f32 v[40:41], v[204:205], v[46:47] op_sel:[0,0] op_sel_hi:[1,0]
	v_pk_mul_f32 v[42:43], v[206:207], v[46:47] op_sel:[0,0] op_sel_hi:[1,0]
	v_exp_f32_e32 v36, v36
	v_exp_f32_e32 v37, v37
	v_exp_f32_e32 v38, v38
	v_exp_f32_e32 v39, v39
	v_exp_f32_e32 v40, v40
	v_exp_f32_e32 v41, v41
	v_exp_f32_e32 v42, v42
	v_exp_f32_e32 v43, v43
	v_pk_add_f32 v[36:37], v[36:37], v[46:47] op_sel:[0,1] op_sel_hi:[1,1]
	v_pk_add_f32 v[38:39], v[38:39], v[46:47] op_sel:[0,1] op_sel_hi:[1,1]
	v_pk_add_f32 v[40:41], v[40:41], v[46:47] op_sel:[0,1] op_sel_hi:[1,1]
	v_pk_add_f32 v[42:43], v[42:43], v[46:47] op_sel:[0,1] op_sel_hi:[1,1]
	v_rcp_f32_e32 v36, v36
	v_rcp_f32_e32 v37, v37
	v_rcp_f32_e32 v38, v38
	v_rcp_f32_e32 v39, v39
	v_rcp_f32_e32 v40, v40
	v_rcp_f32_e32 v41, v41
	v_rcp_f32_e32 v42, v42
	v_rcp_f32_e32 v43, v43
	v_pk_mul_f32 v[36:37], v[200:201], v[36:37]
	v_pk_mul_f32 v[38:39], v[202:203], v[38:39]
	v_pk_mul_f32 v[40:41], v[204:205], v[40:41]
	v_pk_mul_f32 v[42:43], v[206:207], v[42:43]
	v_pk_mul_f32 v[184:185], v[184:185], v[36:37]
	v_pk_mul_f32 v[186:187], v[186:187], v[38:39]
	v_pk_mul_f32 v[188:189], v[188:189], v[40:41]
	v_pk_mul_f32 v[190:191], v[190:191], v[42:43]
	v_pk_fma_f32 v[44:45], v[184:185], v[184:185], v[44:45]
	v_pk_fma_f32 v[44:45], v[186:187], v[186:187], v[44:45]
	v_pk_fma_f32 v[44:45], v[188:189], v[188:189], v[44:45]
	v_pk_fma_f32 v[44:45], v[190:191], v[190:191], v[44:45]
	v_cvt_pk_bf16_f32 v160, v184, v185
	v_cvt_pk_bf16_f32 v161, v186, v187
	v_cvt_pk_bf16_f32 v162, v188, v189
	v_cvt_pk_bf16_f32 v163, v190, v191
	v_lshlrev_b32_e32 v184, 16, v68
	v_and_b32_e32 v185, 0xffff0000, v68
	v_lshlrev_b32_e32 v186, 16, v69
	v_and_b32_e32 v187, 0xffff0000, v69
	v_lshlrev_b32_e32 v188, 16, v70
	v_and_b32_e32 v189, 0xffff0000, v70
	v_lshlrev_b32_e32 v190, 16, v71
	v_and_b32_e32 v191, 0xffff0000, v71
	v_lshlrev_b32_e32 v192, 16, v84
	v_and_b32_e32 v193, 0xffff0000, v84
	v_lshlrev_b32_e32 v194, 16, v85
	v_and_b32_e32 v195, 0xffff0000, v85
	v_lshlrev_b32_e32 v196, 16, v86
	v_and_b32_e32 v197, 0xffff0000, v86
	v_lshlrev_b32_e32 v198, 16, v87
	v_and_b32_e32 v199, 0xffff0000, v87
	v_lshlrev_b32_e32 v200, 16, v100
	v_and_b32_e32 v201, 0xffff0000, v100
	v_lshlrev_b32_e32 v202, 16, v101
	v_and_b32_e32 v203, 0xffff0000, v101
	v_lshlrev_b32_e32 v204, 16, v102
	v_and_b32_e32 v205, 0xffff0000, v102
	v_lshlrev_b32_e32 v206, 16, v103
	v_and_b32_e32 v207, 0xffff0000, v103
	v_pk_fma_f32 v[184:185], v[192:193], v[34:35], v[184:185] op_sel:[0,1,0] op_sel_hi:[1,1,1]
	v_pk_fma_f32 v[186:187], v[194:195], v[34:35], v[186:187] op_sel:[0,1,0] op_sel_hi:[1,1,1]
	v_pk_fma_f32 v[188:189], v[196:197], v[34:35], v[188:189] op_sel:[0,1,0] op_sel_hi:[1,1,1]
	v_pk_fma_f32 v[190:191], v[198:199], v[34:35], v[190:191] op_sel:[0,1,0] op_sel_hi:[1,1,1]
	v_pk_mul_f32 v[36:37], v[200:201], v[46:47] op_sel:[0,0] op_sel_hi:[1,0]
	v_pk_mul_f32 v[38:39], v[202:203], v[46:47] op_sel:[0,0] op_sel_hi:[1,0]
	v_pk_mul_f32 v[40:41], v[204:205], v[46:47] op_sel:[0,0] op_sel_hi:[1,0]
	v_pk_mul_f32 v[42:43], v[206:207], v[46:47] op_sel:[0,0] op_sel_hi:[1,0]
	v_exp_f32_e32 v36, v36
	v_exp_f32_e32 v37, v37
	v_exp_f32_e32 v38, v38
	v_exp_f32_e32 v39, v39
	v_exp_f32_e32 v40, v40
	v_exp_f32_e32 v41, v41
	v_exp_f32_e32 v42, v42
	v_exp_f32_e32 v43, v43
	v_pk_add_f32 v[36:37], v[36:37], v[46:47] op_sel:[0,1] op_sel_hi:[1,1]
	v_pk_add_f32 v[38:39], v[38:39], v[46:47] op_sel:[0,1] op_sel_hi:[1,1]
	v_pk_add_f32 v[40:41], v[40:41], v[46:47] op_sel:[0,1] op_sel_hi:[1,1]
	v_pk_add_f32 v[42:43], v[42:43], v[46:47] op_sel:[0,1] op_sel_hi:[1,1]
	v_rcp_f32_e32 v36, v36
	v_rcp_f32_e32 v37, v37
	v_rcp_f32_e32 v38, v38
	v_rcp_f32_e32 v39, v39
	v_rcp_f32_e32 v40, v40
	v_rcp_f32_e32 v41, v41
	v_rcp_f32_e32 v42, v42
	v_rcp_f32_e32 v43, v43
	v_pk_mul_f32 v[36:37], v[200:201], v[36:37]
	v_pk_mul_f32 v[38:39], v[202:203], v[38:39]
	v_pk_mul_f32 v[40:41], v[204:205], v[40:41]
	v_pk_mul_f32 v[42:43], v[206:207], v[42:43]
	v_pk_mul_f32 v[184:185], v[184:185], v[36:37]
	v_pk_mul_f32 v[186:187], v[186:187], v[38:39]
	v_pk_mul_f32 v[188:189], v[188:189], v[40:41]
	v_pk_mul_f32 v[190:191], v[190:191], v[42:43]
	v_pk_fma_f32 v[44:45], v[184:185], v[184:185], v[44:45]
	v_pk_fma_f32 v[44:45], v[186:187], v[186:187], v[44:45]
	v_pk_fma_f32 v[44:45], v[188:189], v[188:189], v[44:45]
	v_pk_fma_f32 v[44:45], v[190:191], v[190:191], v[44:45]
	v_cvt_pk_bf16_f32 v164, v184, v185
	v_cvt_pk_bf16_f32 v165, v186, v187
	v_cvt_pk_bf16_f32 v166, v188, v189
	v_cvt_pk_bf16_f32 v167, v190, v191
	v_add_f32_e32 v208, v44, v45
	s_nop 1
	v_add_f32_dpp v209, v208, v208 quad_perm:[1,0,3,2] row_mask:0xf bank_mask:0xf
	s_nop 1
	v_add_f32_dpp v208, v209, v209 quad_perm:[2,3,0,1] row_mask:0xf bank_mask:0xf
	s_nop 1
	v_add_f32_dpp v209, v208, v208 row_half_mirror row_mask:0xf bank_mask:0xf
	s_nop 1
	v_add_f32_dpp v208, v209, v209 row_mirror row_mask:0xf bank_mask:0xf
	s_nop 1
	v_readlane_b32 s10, v208, 0
	v_readlane_b32 s11, v208, 16
	v_readlane_b32 s17, v208, 32
	v_readlane_b32 s24, v208, 48
	s_nop 3
	v_mov_b32_e32 v208, s10
	v_add_f32_e32 v208, s11, v208
	v_add_f32_e32 v208, s17, v208
	v_add_f32_e32 v208, s24, v208
	v_fmamk_f32 v208, v208, 0x3a000000, v48
	v_rsq_f32_e32 v49, v208
	s_nop 0
	v_lshlrev_b32_e32 v184, 16, v152
	v_and_b32_e32 v185, 0xffff0000, v152
	v_lshlrev_b32_e32 v186, 16, v153
	v_and_b32_e32 v187, 0xffff0000, v153
	v_lshlrev_b32_e32 v188, 16, v154
	v_and_b32_e32 v189, 0xffff0000, v154
	v_lshlrev_b32_e32 v190, 16, v155
	v_and_b32_e32 v191, 0xffff0000, v155
; __device__ __forceinline__ float siluf_(float x) { return x * __builtin_amdgcn_rcpf(1.f + __expf(-x)); }
; __device__ __forceinline__ void mix_finalize_ssd(size_t row, bf16_t* MIX, const bf16_t* XBC, const bf16_t* PROJ, const float* d_skip, const float* ssd_norm_w, int lane, bf16_t* ssd_dst) {
;     ...
;         for (int k = 0; k < 4; ++k) { float f[8], xf[8], zf[8]; unpack8(yv[k], f); unpack8(xv[k], xf); unpack8(zv[k], zf);
; #pragma unroll
;             for (int e = 0; e < 8; ++e) { f[e] = (f[e] + dsk[k] * xf[e]) * siluf_(zf[e]); s += f[e] * f[e]; }
;             yv[k] = pack8(f); }
;     ...
;         for (int k = 0; k < 4; ++k) { const int c = (k * 64 + lane) * 8;
;             const f32x4 w0 = *(const f32x4*)(ssd_norm_w + c), w1 = *(const f32x4*)(ssd_norm_w + c + 4);
;             const u32x4 yk = (k == 0) ? yv[0] : (k == 1) ? yv[1] : (k == 2) ? yv[2] : yv[3];
;             float f[8]; unpack8(yk, f);
;             float o[8]; o[0] = f[0] * r * w0.x; o[1] = f[1] * r * w0.y; o[2] = f[2] * r * w0.z; o[3] = f[3] * r * w0.w;
;             o[4] = f[4] * r * w1.x; o[5] = f[5] * r * w1.y; o[6] = f[6] * r * w1.z; o[7] = f[7] * r * w1.w;
;             *(u32x4*)(ssd_dst + c) = pack8(o); }
	v_pk_mul_f32 v[184:185], v[184:185], v[48:49] op_sel:[0,1] op_sel_hi:[1,1]
	v_pk_mul_f32 v[186:187], v[186:187], v[48:49] op_sel:[0,1] op_sel_hi:[1,1]
	v_pk_mul_f32 v[188:189], v[188:189], v[48:49] op_sel:[0,1] op_sel_hi:[1,1]
	v_pk_mul_f32 v[190:191], v[190:191], v[48:49] op_sel:[0,1] op_sel_hi:[1,1]
	v_pk_mul_f32 v[184:185], v[184:185], v[0:1]
	v_pk_mul_f32 v[186:187], v[186:187], v[2:3]
	v_pk_mul_f32 v[188:189], v[188:189], v[4:5]
	v_pk_mul_f32 v[190:191], v[190:191], v[6:7]
	v_cvt_pk_bf16_f32 v168, v184, v185
	v_cvt_pk_bf16_f32 v169, v186, v187
	v_cvt_pk_bf16_f32 v170, v188, v189
	v_cvt_pk_bf16_f32 v171, v190, v191
	global_store_dwordx4 v50, v[168:171], s[26:27] offset:0
	v_lshlrev_b32_e32 v184, 16, v156
	v_and_b32_e32 v185, 0xffff0000, v156
	v_lshlrev_b32_e32 v186, 16, v157
	v_and_b32_e32 v187, 0xffff0000, v157
	v_lshlrev_b32_e32 v188, 16, v158
	v_and_b32_e32 v189, 0xffff0000, v158
	v_lshlrev_b32_e32 v190, 16, v159
	v_and_b32_e32 v191, 0xffff0000, v159
	v_pk_mul_f32 v[184:185], v[184:185], v[48:49] op_sel:[0,1] op_sel_hi:[1,1]
	v_pk_mul_f32 v[186:187], v[186:187], v[48:49] op_sel:[0,1] op_sel_hi:[1,1]
	v_pk_mul_f32 v[188:189], v[188:189], v[48:49] op_sel:[0,1] op_sel_hi:[1,1]
	v_pk_mul_f32 v[190:191], v[190:191], v[48:49] op_sel:[0,1] op_sel_hi:[1,1]
	v_pk_mul_f32 v[184:185], v[184:185], v[8:9]
	v_pk_mul_f32 v[186:187], v[186:187], v[10:11]
	v_pk_mul_f32 v[188:189], v[188:189], v[12:13]
	v_pk_mul_f32 v[190:191], v[190:191], v[14:15]
	v_cvt_pk_bf16_f32 v172, v184, v185
	v_cvt_pk_bf16_f32 v173, v186, v187
	v_cvt_pk_bf16_f32 v174, v188, v189
	v_cvt_pk_bf16_f32 v175, v190, v191
	global_store_dwordx4 v50, v[172:175], s[26:27] offset:1024
	v_lshlrev_b32_e32 v184, 16, v160
	v_and_b32_e32 v185, 0xffff0000, v160
	v_lshlrev_b32_e32 v186, 16, v161
	v_and_b32_e32 v187, 0xffff0000, v161
	v_lshlrev_b32_e32 v188, 16, v162
	v_and_b32_e32 v189, 0xffff0000, v162
	v_lshlrev_b32_e32 v190, 16, v163
	v_and_b32_e32 v191, 0xffff0000, v163
	v_pk_mul_f32 v[184:185], v[184:185], v[48:49] op_sel:[0,1] op_sel_hi:[1,1]
	v_pk_mul_f32 v[186:187], v[186:187], v[48:49] op_sel:[0,1] op_sel_hi:[1,1]
	v_pk_mul_f32 v[188:189], v[188:189], v[48:49] op_sel:[0,1] op_sel_hi:[1,1]
	v_pk_mul_f32 v[190:191], v[190:191], v[48:49] op_sel:[0,1] op_sel_hi:[1,1]
	v_pk_mul_f32 v[184:185], v[184:185], v[16:17]
	v_pk_mul_f32 v[186:187], v[186:187], v[18:19]
	v_pk_mul_f32 v[188:189], v[188:189], v[20:21]
	v_pk_mul_f32 v[190:191], v[190:191], v[22:23]
	v_cvt_pk_bf16_f32 v176, v184, v185
	v_cvt_pk_bf16_f32 v177, v186, v187
	v_cvt_pk_bf16_f32 v178, v188, v189
	v_cvt_pk_bf16_f32 v179, v190, v191
	global_store_dwordx4 v50, v[176:179], s[26:27] offset:2048
	v_lshlrev_b32_e32 v184, 16, v164
	v_and_b32_e32 v185, 0xffff0000, v164
	v_lshlrev_b32_e32 v186, 16, v165
	v_and_b32_e32 v187, 0xffff0000, v165
	v_lshlrev_b32_e32 v188, 16, v166
	v_and_b32_e32 v189, 0xffff0000, v166
	v_lshlrev_b32_e32 v190, 16, v167
	v_and_b32_e32 v191, 0xffff0000, v167
	v_pk_mul_f32 v[184:185], v[184:185], v[48:49] op_sel:[0,1] op_sel_hi:[1,1]
	v_pk_mul_f32 v[186:187], v[186:187], v[48:49] op_sel:[0,1] op_sel_hi:[1,1]
	v_pk_mul_f32 v[188:189], v[188:189], v[48:49] op_sel:[0,1] op_sel_hi:[1,1]
	v_pk_mul_f32 v[190:191], v[190:191], v[48:49] op_sel:[0,1] op_sel_hi:[1,1]
	v_pk_mul_f32 v[184:185], v[184:185], v[24:25]
	v_pk_mul_f32 v[186:187], v[186:187], v[26:27]
	v_pk_mul_f32 v[188:189], v[188:189], v[28:29]
	v_pk_mul_f32 v[190:191], v[190:191], v[30:31]
	v_cvt_pk_bf16_f32 v180, v184, v185
	v_cvt_pk_bf16_f32 v181, v186, v187
	v_cvt_pk_bf16_f32 v182, v188, v189
	v_cvt_pk_bf16_f32 v183, v190, v191
	global_store_dwordx4 v50, v[180:183], s[26:27] offset:3072
	s_waitcnt vmcnt(4)
	v_mov_b32_e32 v44, 0
	v_mov_b32_e32 v45, 0
	v_lshlrev_b32_e32 v184, 16, v104
	v_and_b32_e32 v185, 0xffff0000, v104
	v_lshlrev_b32_e32 v186, 16, v105
	v_and_b32_e32 v187, 0xffff0000, v105
	v_lshlrev_b32_e32 v188, 16, v106
	v_and_b32_e32 v189, 0xffff0000, v106
	v_lshlrev_b32_e32 v190, 16, v107
	v_and_b32_e32 v191, 0xffff0000, v107
	v_lshlrev_b32_e32 v192, 16, v120
	v_and_b32_e32 v193, 0xffff0000, v120
	v_lshlrev_b32_e32 v194, 16, v121
	v_and_b32_e32 v195, 0xffff0000, v121
	v_lshlrev_b32_e32 v196, 16, v122
	v_and_b32_e32 v197, 0xffff0000, v122
	v_lshlrev_b32_e32 v198, 16, v123
	v_and_b32_e32 v199, 0xffff0000, v123
	v_lshlrev_b32_e32 v200, 16, v136
	v_and_b32_e32 v201, 0xffff0000, v136
	v_lshlrev_b32_e32 v202, 16, v137
	v_and_b32_e32 v203, 0xffff0000, v137
	v_lshlrev_b32_e32 v204, 16, v138
	v_and_b32_e32 v205, 0xffff0000, v138
	v_lshlrev_b32_e32 v206, 16, v139
	v_and_b32_e32 v207, 0xffff0000, v139
	v_pk_fma_f32 v[184:185], v[192:193], v[32:33], v[184:185] op_sel:[0,0,0] op_sel_hi:[1,0,1]
	v_pk_fma_f32 v[186:187], v[194:195], v[32:33], v[186:187] op_sel:[0,0,0] op_sel_hi:[1,0,1]
	v_pk_fma_f32 v[188:189], v[196:197], v[32:33], v[188:189] op_sel:[0,0,0] op_sel_hi:[1,0,1]
	v_pk_fma_f32 v[190:191], v[198:199], v[32:33], v[190:191] op_sel:[0,0,0] op_sel_hi:[1,0,1]
	v_pk_mul_f32 v[36:37], v[200:201], v[46:47] op_sel:[0,0] op_sel_hi:[1,0]
	v_pk_mul_f32 v[38:39], v[202:203], v[46:47] op_sel:[0,0] op_sel_hi:[1,0]
	v_pk_mul_f32 v[40:41], v[204:205], v[46:47] op_sel:[0,0] op_sel_hi:[1,0]
	v_pk_mul_f32 v[42:43], v[206:207], v[46:47] op_sel:[0,0] op_sel_hi:[1,0]
	v_exp_f32_e32 v36, v36
	v_exp_f32_e32 v37, v37
	v_exp_f32_e32 v38, v38
	v_exp_f32_e32 v39, v39
	v_exp_f32_e32 v40, v40
	v_exp_f32_e32 v41, v41
	v_exp_f32_e32 v42, v42
	v_exp_f32_e32 v43, v43
	v_pk_add_f32 v[36:37], v[36:37], v[46:47] op_sel:[0,1] op_sel_hi:[1,1]
	v_pk_add_f32 v[38:39], v[38:39], v[46:47] op_sel:[0,1] op_sel_hi:[1,1]
	v_pk_add_f32 v[40:41], v[40:41], v[46:47] op_sel:[0,1] op_sel_hi:[1,1]
; __device__ __forceinline__ float siluf_(float x) { return x * __builtin_amdgcn_rcpf(1.f + __expf(-x)); }
; __device__ __forceinline__ void mix_finalize_ssd(size_t row, bf16_t* MIX, const bf16_t* XBC, const bf16_t* PROJ, const float* d_skip, const float* ssd_norm_w, int lane, bf16_t* ssd_dst) {
;     ...
;         for (int k = 0; k < 4; ++k) { float f[8], xf[8], zf[8]; unpack8(yv[k], f); unpack8(xv[k], xf); unpack8(zv[k], zf);
; #pragma unroll
;             for (int e = 0; e < 8; ++e) { f[e] = (f[e] + dsk[k] * xf[e]) * siluf_(zf[e]); s += f[e] * f[e]; }
;             yv[k] = pack8(f); }
	v_pk_add_f32 v[42:43], v[42:43], v[46:47] op_sel:[0,1] op_sel_hi:[1,1]
	v_rcp_f32_e32 v36, v36
	v_rcp_f32_e32 v37, v37
	v_rcp_f32_e32 v38, v38
	v_rcp_f32_e32 v39, v39
	v_rcp_f32_e32 v40, v40
	v_rcp_f32_e32 v41, v41
	v_rcp_f32_e32 v42, v42
	v_rcp_f32_e32 v43, v43
	v_pk_mul_f32 v[36:37], v[200:201], v[36:37]
	v_pk_mul_f32 v[38:39], v[202:203], v[38:39]
	v_pk_mul_f32 v[40:41], v[204:205], v[40:41]
	v_pk_mul_f32 v[42:43], v[206:207], v[42:43]
	v_pk_mul_f32 v[184:185], v[184:185], v[36:37]
	v_pk_mul_f32 v[186:187], v[186:187], v[38:39]
	v_pk_mul_f32 v[188:189], v[188:189], v[40:41]
	v_pk_mul_f32 v[190:191], v[190:191], v[42:43]
	v_pk_fma_f32 v[44:45], v[184:185], v[184:185], v[44:45]
	v_pk_fma_f32 v[44:45], v[186:187], v[186:187], v[44:45]
	v_pk_fma_f32 v[44:45], v[188:189], v[188:189], v[44:45]
	v_pk_fma_f32 v[44:45], v[190:191], v[190:191], v[44:45]
	v_cvt_pk_bf16_f32 v152, v184, v185
	v_cvt_pk_bf16_f32 v153, v186, v187
	v_cvt_pk_bf16_f32 v154, v188, v189
	v_cvt_pk_bf16_f32 v155, v190, v191
	v_lshlrev_b32_e32 v184, 16, v108
	v_and_b32_e32 v185, 0xffff0000, v108
	v_lshlrev_b32_e32 v186, 16, v109
	v_and_b32_e32 v187, 0xffff0000, v109
	v_lshlrev_b32_e32 v188, 16, v110
	v_and_b32_e32 v189, 0xffff0000, v110
	v_lshlrev_b32_e32 v190, 16, v111
	v_and_b32_e32 v191, 0xffff0000, v111
	v_lshlrev_b32_e32 v192, 16, v124
	v_and_b32_e32 v193, 0xffff0000, v124
	v_lshlrev_b32_e32 v194, 16, v125
	v_and_b32_e32 v195, 0xffff0000, v125
	v_lshlrev_b32_e32 v196, 16, v126
	v_and_b32_e32 v197, 0xffff0000, v126
	v_lshlrev_b32_e32 v198, 16, v127
	v_and_b32_e32 v199, 0xffff0000, v127
	v_lshlrev_b32_e32 v200, 16, v140
	v_and_b32_e32 v201, 0xffff0000, v140
	v_lshlrev_b32_e32 v202, 16, v141
	v_and_b32_e32 v203, 0xffff0000, v141
	v_lshlrev_b32_e32 v204, 16, v142
	v_and_b32_e32 v205, 0xffff0000, v142
	v_lshlrev_b32_e32 v206, 16, v143
	v_and_b32_e32 v207, 0xffff0000, v143
	v_pk_fma_f32 v[184:185], v[192:193], v[32:33], v[184:185] op_sel:[0,1,0] op_sel_hi:[1,1,1]
	v_pk_fma_f32 v[186:187], v[194:195], v[32:33], v[186:187] op_sel:[0,1,0] op_sel_hi:[1,1,1]
	v_pk_fma_f32 v[188:189], v[196:197], v[32:33], v[188:189] op_sel:[0,1,0] op_sel_hi:[1,1,1]
	v_pk_fma_f32 v[190:191], v[198:199], v[32:33], v[190:191] op_sel:[0,1,0] op_sel_hi:[1,1,1]
	v_pk_mul_f32 v[36:37], v[200:201], v[46:47] op_sel:[0,0] op_sel_hi:[1,0]
	v_pk_mul_f32 v[38:39], v[202:203], v[46:47] op_sel:[0,0] op_sel_hi:[1,0]
	v_pk_mul_f32 v[40:41], v[204:205], v[46:47] op_sel:[0,0] op_sel_hi:[1,0]
	v_pk_mul_f32 v[42:43], v[206:207], v[46:47] op_sel:[0,0] op_sel_hi:[1,0]
	v_exp_f32_e32 v36, v36
	v_exp_f32_e32 v37, v37
	v_exp_f32_e32 v38, v38
	v_exp_f32_e32 v39, v39
	v_exp_f32_e32 v40, v40
	v_exp_f32_e32 v41, v41
	v_exp_f32_e32 v42, v42
	v_exp_f32_e32 v43, v43
	v_pk_add_f32 v[36:37], v[36:37], v[46:47] op_sel:[0,1] op_sel_hi:[1,1]
	v_pk_add_f32 v[38:39], v[38:39], v[46:47] op_sel:[0,1] op_sel_hi:[1,1]
	v_pk_add_f32 v[40:41], v[40:41], v[46:47] op_sel:[0,1] op_sel_hi:[1,1]
	v_pk_add_f32 v[42:43], v[42:43], v[46:47] op_sel:[0,1] op_sel_hi:[1,1]
	v_rcp_f32_e32 v36, v36
	v_rcp_f32_e32 v37, v37
	v_rcp_f32_e32 v38, v38
	v_rcp_f32_e32 v39, v39
	v_rcp_f32_e32 v40, v40
	v_rcp_f32_e32 v41, v41
	v_rcp_f32_e32 v42, v42
	v_rcp_f32_e32 v43, v43
	v_pk_mul_f32 v[36:37], v[200:201], v[36:37]
	v_pk_mul_f32 v[38:39], v[202:203], v[38:39]
	v_pk_mul_f32 v[40:41], v[204:205], v[40:41]
	v_pk_mul_f32 v[42:43], v[206:207], v[42:43]
	v_pk_mul_f32 v[184:185], v[184:185], v[36:37]
	v_pk_mul_f32 v[186:187], v[186:187], v[38:39]
	v_pk_mul_f32 v[188:189], v[188:189], v[40:41]
	v_pk_mul_f32 v[190:191], v[190:191], v[42:43]
	v_pk_fma_f32 v[44:45], v[184:185], v[184:185], v[44:45]
	v_pk_fma_f32 v[44:45], v[186:187], v[186:187], v[44:45]
	v_pk_fma_f32 v[44:45], v[188:189], v[188:189], v[44:45]
	v_pk_fma_f32 v[44:45], v[190:191], v[190:191], v[44:45]
	v_cvt_pk_bf16_f32 v156, v184, v185
	v_cvt_pk_bf16_f32 v157, v186, v187
	v_cvt_pk_bf16_f32 v158, v188, v189
	v_cvt_pk_bf16_f32 v159, v190, v191
	v_lshlrev_b32_e32 v184, 16, v112
	v_and_b32_e32 v185, 0xffff0000, v112
	v_lshlrev_b32_e32 v186, 16, v113
	v_and_b32_e32 v187, 0xffff0000, v113
	v_lshlrev_b32_e32 v188, 16, v114
	v_and_b32_e32 v189, 0xffff0000, v114
	v_lshlrev_b32_e32 v190, 16, v115
	v_and_b32_e32 v191, 0xffff0000, v115
	v_lshlrev_b32_e32 v192, 16, v128
	v_and_b32_e32 v193, 0xffff0000, v128
	v_lshlrev_b32_e32 v194, 16, v129
	v_and_b32_e32 v195, 0xffff0000, v129
	v_lshlrev_b32_e32 v196, 16, v130
	v_and_b32_e32 v197, 0xffff0000, v130
	v_lshlrev_b32_e32 v198, 16, v131
	v_and_b32_e32 v199, 0xffff0000, v131
	v_lshlrev_b32_e32 v200, 16, v144
	v_and_b32_e32 v201, 0xffff0000, v144
	v_lshlrev_b32_e32 v202, 16, v145
	v_and_b32_e32 v203, 0xffff0000, v145
	v_lshlrev_b32_e32 v204, 16, v146
	v_and_b32_e32 v205, 0xffff0000, v146
	v_lshlrev_b32_e32 v206, 16, v147
	v_and_b32_e32 v207, 0xffff0000, v147
	v_pk_fma_f32 v[184:185], v[192:193], v[34:35], v[184:185] op_sel:[0,0,0] op_sel_hi:[1,0,1]
	v_pk_fma_f32 v[186:187], v[194:195], v[34:35], v[186:187] op_sel:[0,0,0] op_sel_hi:[1,0,1]
	v_pk_fma_f32 v[188:189], v[196:197], v[34:35], v[188:189] op_sel:[0,0,0] op_sel_hi:[1,0,1]
	v_pk_fma_f32 v[190:191], v[198:199], v[34:35], v[190:191] op_sel:[0,0,0] op_sel_hi:[1,0,1]
	v_pk_mul_f32 v[36:37], v[200:201], v[46:47] op_sel:[0,0] op_sel_hi:[1,0]
	v_pk_mul_f32 v[38:39], v[202:203], v[46:47] op_sel:[0,0] op_sel_hi:[1,0]
	v_pk_mul_f32 v[40:41], v[204:205], v[46:47] op_sel:[0,0] op_sel_hi:[1,0]
	v_pk_mul_f32 v[42:43], v[206:207], v[46:47] op_sel:[0,0] op_sel_hi:[1,0]
	v_exp_f32_e32 v36, v36
	v_exp_f32_e32 v37, v37
	v_exp_f32_e32 v38, v38
	v_exp_f32_e32 v39, v39
	v_exp_f32_e32 v40, v40
	v_exp_f32_e32 v41, v41
	v_exp_f32_e32 v42, v42
; __device__ __forceinline__ float siluf_(float x) { return x * __builtin_amdgcn_rcpf(1.f + __expf(-x)); }
; __device__ __forceinline__ void mix_finalize_ssd(size_t row, bf16_t* MIX, const bf16_t* XBC, const bf16_t* PROJ, const float* d_skip, const float* ssd_norm_w, int lane, bf16_t* ssd_dst) {
;     ...
;         for (int k = 0; k < 4; ++k) { float f[8], xf[8], zf[8]; unpack8(yv[k], f); unpack8(xv[k], xf); unpack8(zv[k], zf);
; #pragma unroll
;             for (int e = 0; e < 8; ++e) { f[e] = (f[e] + dsk[k] * xf[e]) * siluf_(zf[e]); s += f[e] * f[e]; }
;             yv[k] = pack8(f); }
;         const float r = rsqrtf(wave_sum(s) * (1.f / DM) + EPS);
	v_exp_f32_e32 v43, v43
	v_pk_add_f32 v[36:37], v[36:37], v[46:47] op_sel:[0,1] op_sel_hi:[1,1]
	v_pk_add_f32 v[38:39], v[38:39], v[46:47] op_sel:[0,1] op_sel_hi:[1,1]
	v_pk_add_f32 v[40:41], v[40:41], v[46:47] op_sel:[0,1] op_sel_hi:[1,1]
	v_pk_add_f32 v[42:43], v[42:43], v[46:47] op_sel:[0,1] op_sel_hi:[1,1]
	v_rcp_f32_e32 v36, v36
	v_rcp_f32_e32 v37, v37
	v_rcp_f32_e32 v38, v38
	v_rcp_f32_e32 v39, v39
	v_rcp_f32_e32 v40, v40
	v_rcp_f32_e32 v41, v41
	v_rcp_f32_e32 v42, v42
	v_rcp_f32_e32 v43, v43
	v_pk_mul_f32 v[36:37], v[200:201], v[36:37]
	v_pk_mul_f32 v[38:39], v[202:203], v[38:39]
	v_pk_mul_f32 v[40:41], v[204:205], v[40:41]
	v_pk_mul_f32 v[42:43], v[206:207], v[42:43]
	v_pk_mul_f32 v[184:185], v[184:185], v[36:37]
	v_pk_mul_f32 v[186:187], v[186:187], v[38:39]
	v_pk_mul_f32 v[188:189], v[188:189], v[40:41]
	v_pk_mul_f32 v[190:191], v[190:191], v[42:43]
	v_pk_fma_f32 v[44:45], v[184:185], v[184:185], v[44:45]
	v_pk_fma_f32 v[44:45], v[186:187], v[186:187], v[44:45]
	v_pk_fma_f32 v[44:45], v[188:189], v[188:189], v[44:45]
	v_pk_fma_f32 v[44:45], v[190:191], v[190:191], v[44:45]
	v_cvt_pk_bf16_f32 v160, v184, v185
	v_cvt_pk_bf16_f32 v161, v186, v187
	v_cvt_pk_bf16_f32 v162, v188, v189
	v_cvt_pk_bf16_f32 v163, v190, v191
	v_lshlrev_b32_e32 v184, 16, v116
	v_and_b32_e32 v185, 0xffff0000, v116
	v_lshlrev_b32_e32 v186, 16, v117
	v_and_b32_e32 v187, 0xffff0000, v117
	v_lshlrev_b32_e32 v188, 16, v118
	v_and_b32_e32 v189, 0xffff0000, v118
	v_lshlrev_b32_e32 v190, 16, v119
	v_and_b32_e32 v191, 0xffff0000, v119
	v_lshlrev_b32_e32 v192, 16, v132
	v_and_b32_e32 v193, 0xffff0000, v132
	v_lshlrev_b32_e32 v194, 16, v133
	v_and_b32_e32 v195, 0xffff0000, v133
	v_lshlrev_b32_e32 v196, 16, v134
	v_and_b32_e32 v197, 0xffff0000, v134
	v_lshlrev_b32_e32 v198, 16, v135
	v_and_b32_e32 v199, 0xffff0000, v135
	v_lshlrev_b32_e32 v200, 16, v148
	v_and_b32_e32 v201, 0xffff0000, v148
	v_lshlrev_b32_e32 v202, 16, v149
	v_and_b32_e32 v203, 0xffff0000, v149
	v_lshlrev_b32_e32 v204, 16, v150
	v_and_b32_e32 v205, 0xffff0000, v150
	v_lshlrev_b32_e32 v206, 16, v151
	v_and_b32_e32 v207, 0xffff0000, v151
	v_pk_fma_f32 v[184:185], v[192:193], v[34:35], v[184:185] op_sel:[0,1,0] op_sel_hi:[1,1,1]
	v_pk_fma_f32 v[186:187], v[194:195], v[34:35], v[186:187] op_sel:[0,1,0] op_sel_hi:[1,1,1]
	v_pk_fma_f32 v[188:189], v[196:197], v[34:35], v[188:189] op_sel:[0,1,0] op_sel_hi:[1,1,1]
	v_pk_fma_f32 v[190:191], v[198:199], v[34:35], v[190:191] op_sel:[0,1,0] op_sel_hi:[1,1,1]
	v_pk_mul_f32 v[36:37], v[200:201], v[46:47] op_sel:[0,0] op_sel_hi:[1,0]
	v_pk_mul_f32 v[38:39], v[202:203], v[46:47] op_sel:[0,0] op_sel_hi:[1,0]
	v_pk_mul_f32 v[40:41], v[204:205], v[46:47] op_sel:[0,0] op_sel_hi:[1,0]
	v_pk_mul_f32 v[42:43], v[206:207], v[46:47] op_sel:[0,0] op_sel_hi:[1,0]
	v_exp_f32_e32 v36, v36
	v_exp_f32_e32 v37, v37
	v_exp_f32_e32 v38, v38
	v_exp_f32_e32 v39, v39
	v_exp_f32_e32 v40, v40
	v_exp_f32_e32 v41, v41
	v_exp_f32_e32 v42, v42
	v_exp_f32_e32 v43, v43
	v_pk_add_f32 v[36:37], v[36:37], v[46:47] op_sel:[0,1] op_sel_hi:[1,1]
	v_pk_add_f32 v[38:39], v[38:39], v[46:47] op_sel:[0,1] op_sel_hi:[1,1]
	v_pk_add_f32 v[40:41], v[40:41], v[46:47] op_sel:[0,1] op_sel_hi:[1,1]
	v_pk_add_f32 v[42:43], v[42:43], v[46:47] op_sel:[0,1] op_sel_hi:[1,1]
	v_rcp_f32_e32 v36, v36
	v_rcp_f32_e32 v37, v37
	v_rcp_f32_e32 v38, v38
	v_rcp_f32_e32 v39, v39
	v_rcp_f32_e32 v40, v40
	v_rcp_f32_e32 v41, v41
	v_rcp_f32_e32 v42, v42
	v_rcp_f32_e32 v43, v43
	v_pk_mul_f32 v[36:37], v[200:201], v[36:37]
	v_pk_mul_f32 v[38:39], v[202:203], v[38:39]
	v_pk_mul_f32 v[40:41], v[204:205], v[40:41]
	v_pk_mul_f32 v[42:43], v[206:207], v[42:43]
	v_pk_mul_f32 v[184:185], v[184:185], v[36:37]
	v_pk_mul_f32 v[186:187], v[186:187], v[38:39]
	v_pk_mul_f32 v[188:189], v[188:189], v[40:41]
	v_pk_mul_f32 v[190:191], v[190:191], v[42:43]
	v_pk_fma_f32 v[44:45], v[184:185], v[184:185], v[44:45]
	v_pk_fma_f32 v[44:45], v[186:187], v[186:187], v[44:45]
	v_pk_fma_f32 v[44:45], v[188:189], v[188:189], v[44:45]
	v_pk_fma_f32 v[44:45], v[190:191], v[190:191], v[44:45]
	v_cvt_pk_bf16_f32 v164, v184, v185
	v_cvt_pk_bf16_f32 v165, v186, v187
	v_cvt_pk_bf16_f32 v166, v188, v189
	v_cvt_pk_bf16_f32 v167, v190, v191
	v_add_f32_e32 v208, v44, v45
	s_nop 1
	v_add_f32_dpp v209, v208, v208 quad_perm:[1,0,3,2] row_mask:0xf bank_mask:0xf
	s_nop 1
	v_add_f32_dpp v208, v209, v209 quad_perm:[2,3,0,1] row_mask:0xf bank_mask:0xf
	s_nop 1
; __device__ __forceinline__ void mix_finalize_ssd(size_t row, bf16_t* MIX, const bf16_t* XBC, const bf16_t* PROJ, const float* d_skip, const float* ssd_norm_w, int lane, bf16_t* ssd_dst) {
;     ...
;         const float r = rsqrtf(wave_sum(s) * (1.f / DM) + EPS);
; #pragma unroll 1
;         for (int k = 0; k < 4; ++k) { const int c = (k * 64 + lane) * 8;
;             const f32x4 w0 = *(const f32x4*)(ssd_norm_w + c), w1 = *(const f32x4*)(ssd_norm_w + c + 4);
;             const u32x4 yk = (k == 0) ? yv[0] : (k == 1) ? yv[1] : (k == 2) ? yv[2] : yv[3];
;             float f[8]; unpack8(yk, f);
;             float o[8]; o[0] = f[0] * r * w0.x; o[1] = f[1] * r * w0.y; o[2] = f[2] * r * w0.z; o[3] = f[3] * r * w0.w;
;             o[4] = f[4] * r * w1.x; o[5] = f[5] * r * w1.y; o[6] = f[6] * r * w1.z; o[7] = f[7] * r * w1.w;
;             *(u32x4*)(ssd_dst + c) = pack8(o); }
	v_add_f32_dpp v209, v208, v208 row_half_mirror row_mask:0xf bank_mask:0xf
	s_nop 1
	v_add_f32_dpp v208, v209, v209 row_mirror row_mask:0xf bank_mask:0xf
	s_nop 1
	v_readlane_b32 s10, v208, 0
	v_readlane_b32 s11, v208, 16
	v_readlane_b32 s17, v208, 32
	v_readlane_b32 s24, v208, 48
	s_nop 3
	v_mov_b32_e32 v208, s10
	v_add_f32_e32 v208, s11, v208
	v_add_f32_e32 v208, s17, v208
	v_add_f32_e32 v208, s24, v208
	v_fmamk_f32 v208, v208, 0x3a000000, v48
	v_rsq_f32_e32 v49, v208
	s_nop 0
	v_lshlrev_b32_e32 v184, 16, v152
	v_and_b32_e32 v185, 0xffff0000, v152
	v_lshlrev_b32_e32 v186, 16, v153
	v_and_b32_e32 v187, 0xffff0000, v153
	v_lshlrev_b32_e32 v188, 16, v154
	v_and_b32_e32 v189, 0xffff0000, v154
	v_lshlrev_b32_e32 v190, 16, v155
	v_and_b32_e32 v191, 0xffff0000, v155
	v_pk_mul_f32 v[184:185], v[184:185], v[48:49] op_sel:[0,1] op_sel_hi:[1,1]
	v_pk_mul_f32 v[186:187], v[186:187], v[48:49] op_sel:[0,1] op_sel_hi:[1,1]
	v_pk_mul_f32 v[188:189], v[188:189], v[48:49] op_sel:[0,1] op_sel_hi:[1,1]
	v_pk_mul_f32 v[190:191], v[190:191], v[48:49] op_sel:[0,1] op_sel_hi:[1,1]
	v_pk_mul_f32 v[184:185], v[184:185], v[0:1]
	v_pk_mul_f32 v[186:187], v[186:187], v[2:3]
	v_pk_mul_f32 v[188:189], v[188:189], v[4:5]
	v_pk_mul_f32 v[190:191], v[190:191], v[6:7]
	v_cvt_pk_bf16_f32 v168, v184, v185
	v_cvt_pk_bf16_f32 v169, v186, v187
	v_cvt_pk_bf16_f32 v170, v188, v189
	v_cvt_pk_bf16_f32 v171, v190, v191
	global_store_dwordx4 v50, v[168:171], s[12:13] offset:0
	v_lshlrev_b32_e32 v184, 16, v156
	v_and_b32_e32 v185, 0xffff0000, v156
	v_lshlrev_b32_e32 v186, 16, v157
	v_and_b32_e32 v187, 0xffff0000, v157
	v_lshlrev_b32_e32 v188, 16, v158
	v_and_b32_e32 v189, 0xffff0000, v158
	v_lshlrev_b32_e32 v190, 16, v159
	v_and_b32_e32 v191, 0xffff0000, v159
	v_pk_mul_f32 v[184:185], v[184:185], v[48:49] op_sel:[0,1] op_sel_hi:[1,1]
	v_pk_mul_f32 v[186:187], v[186:187], v[48:49] op_sel:[0,1] op_sel_hi:[1,1]
	v_pk_mul_f32 v[188:189], v[188:189], v[48:49] op_sel:[0,1] op_sel_hi:[1,1]
	v_pk_mul_f32 v[190:191], v[190:191], v[48:49] op_sel:[0,1] op_sel_hi:[1,1]
	v_pk_mul_f32 v[184:185], v[184:185], v[8:9]
	v_pk_mul_f32 v[186:187], v[186:187], v[10:11]
	v_pk_mul_f32 v[188:189], v[188:189], v[12:13]
	v_pk_mul_f32 v[190:191], v[190:191], v[14:15]
	v_cvt_pk_bf16_f32 v172, v184, v185
	v_cvt_pk_bf16_f32 v173, v186, v187
	v_cvt_pk_bf16_f32 v174, v188, v189
	v_cvt_pk_bf16_f32 v175, v190, v191
	global_store_dwordx4 v50, v[172:175], s[12:13] offset:1024
	v_lshlrev_b32_e32 v184, 16, v160
	v_and_b32_e32 v185, 0xffff0000, v160
	v_lshlrev_b32_e32 v186, 16, v161
	v_and_b32_e32 v187, 0xffff0000, v161
	v_lshlrev_b32_e32 v188, 16, v162
	v_and_b32_e32 v189, 0xffff0000, v162
	v_lshlrev_b32_e32 v190, 16, v163
	v_and_b32_e32 v191, 0xffff0000, v163
	v_pk_mul_f32 v[184:185], v[184:185], v[48:49] op_sel:[0,1] op_sel_hi:[1,1]
	v_pk_mul_f32 v[186:187], v[186:187], v[48:49] op_sel:[0,1] op_sel_hi:[1,1]
	v_pk_mul_f32 v[188:189], v[188:189], v[48:49] op_sel:[0,1] op_sel_hi:[1,1]
	v_pk_mul_f32 v[190:191], v[190:191], v[48:49] op_sel:[0,1] op_sel_hi:[1,1]
	v_pk_mul_f32 v[184:185], v[184:185], v[16:17]
	v_pk_mul_f32 v[186:187], v[186:187], v[18:19]
	v_pk_mul_f32 v[188:189], v[188:189], v[20:21]
	v_pk_mul_f32 v[190:191], v[190:191], v[22:23]
	v_cvt_pk_bf16_f32 v176, v184, v185
	v_cvt_pk_bf16_f32 v177, v186, v187
	v_cvt_pk_bf16_f32 v178, v188, v189
	v_cvt_pk_bf16_f32 v179, v190, v191
	global_store_dwordx4 v50, v[176:179], s[12:13] offset:2048
	v_lshlrev_b32_e32 v184, 16, v164
	v_and_b32_e32 v185, 0xffff0000, v164
	v_lshlrev_b32_e32 v186, 16, v165
	v_and_b32_e32 v187, 0xffff0000, v165
	v_lshlrev_b32_e32 v188, 16, v166
	v_and_b32_e32 v189, 0xffff0000, v166
	v_lshlrev_b32_e32 v190, 16, v167
	v_and_b32_e32 v191, 0xffff0000, v167
	v_pk_mul_f32 v[184:185], v[184:185], v[48:49] op_sel:[0,1] op_sel_hi:[1,1]
	v_pk_mul_f32 v[186:187], v[186:187], v[48:49] op_sel:[0,1] op_sel_hi:[1,1]
	v_pk_mul_f32 v[188:189], v[188:189], v[48:49] op_sel:[0,1] op_sel_hi:[1,1]
	v_pk_mul_f32 v[190:191], v[190:191], v[48:49] op_sel:[0,1] op_sel_hi:[1,1]
	v_pk_mul_f32 v[184:185], v[184:185], v[24:25]
	v_pk_mul_f32 v[186:187], v[186:187], v[26:27]
	v_pk_mul_f32 v[188:189], v[188:189], v[28:29]
	v_pk_mul_f32 v[190:191], v[190:191], v[30:31]
	v_cvt_pk_bf16_f32 v180, v184, v185
	v_cvt_pk_bf16_f32 v181, v186, v187
	v_cvt_pk_bf16_f32 v182, v188, v189
	v_cvt_pk_bf16_f32 v183, v190, v191
	global_store_dwordx4 v50, v[180:183], s[12:13] offset:3072
